# MLA key/value buffer (KVB) stored head-major [head][row][128] (256 B row pitch) instead of [row][1024] (2 KiB pitch): P3b epilogue writes it, MLA-unit K/V DMA addressing reads it; x3 dense-attention p
# speedup vs baseline: 1.0072x; 1.0017x over previous
.LBB0_459:
	s_mov_b64 s[98:99], 0x800000
	v_lshl_add_u32 v144, s4, 8, v146
	v_ashrrev_i32_e32 v145, 31, v144
	v_lshlrev_b64 v[142:143], 6, v[144:145]
	v_lshl_add_u64 v[142:143], v[128:129], 0, v[142:143]
	global_load_dwordx4 v[156:159], v[142:143], off
	v_and_b32_e32 v155, 64, v152
	v_xor_b32_e32 v143, 16, v152
	v_add_u32_e32 v163, 64, v155
	v_cmp_lt_i32_e32 vcc, v143, v163
	v_xor_b32_e32 v162, 32, v152
	v_lshl_or_b32 v142, s5, 23, v148
	v_cndmask_b32_e32 v143, v152, v143, vcc
	v_lshlrev_b32_e32 v155, 2, v143
	v_cmp_lt_i32_e32 vcc, v162, v163
	v_ashrrev_i32_e32 v143, 31, v142
	v_lshlrev_b64 v[142:143], 1, v[142:143]
	s_waitcnt vmcnt(0)
	v_mov_b32_e32 v160, v157
	v_mov_b32_e32 v161, v158
	v_mov_b32_e32 v157, v159
	v_pk_add_f32 v[156:157], v[160:161], v[156:157]
	v_lshlrev_b64 v[160:161], 8, v[144:145]
	v_add_f32_e32 v157, v156, v157
	ds_bpermute_b32 v158, v155, v157
	v_cndmask_b32_e32 v156, v152, v162, vcc
	v_lshlrev_b32_e32 v156, 2, v156
	v_lshl_add_u64 v[160:161], s[12:13], 0, v[160:161]
	v_lshl_add_u64 v[160:161], v[160:161], 0, v[142:143]
	s_waitcnt lgkmcnt(0)
	v_add_f32_e32 v157, v157, v158
	ds_bpermute_b32 v162, v156, v157
	v_or_b32_e32 v158, 16, v144
	v_ashrrev_i32_e32 v159, 31, v158
	s_waitcnt lgkmcnt(0)
	v_add_f32_e32 v145, v157, v162
	v_fmamk_f32 v145, v145, 0x3b800000, v153
	v_lshlrev_b64 v[162:163], 6, v[158:159]
	v_lshl_add_u64 v[162:163], v[128:129], 0, v[162:163]
	v_rsq_f32_e32 v167, v145
	v_mul_f32_e32 v166, 0.5, v145
	v_mul_f32_e32 v164, v167, v167
	v_fma_f32 v166, -v166, v164, 0.5
	v_fma_f32 v164, v167, v166, v167
	v_pk_mul_f32 v[126:127], v[126:127], v[164:165] op_sel_hi:[1,0]
	v_pk_mul_f32 v[124:125], v[124:125], v[164:165] op_sel_hi:[1,0]
	v_pk_mul_f32 v[122:123], v[122:123], v[164:165] op_sel_hi:[1,0]
	v_pk_mul_f32 v[120:121], v[120:121], v[164:165] op_sel_hi:[1,0]
	v_pk_mul_f32 v[118:119], v[118:119], v[164:165] op_sel_hi:[1,0]
	v_pk_mul_f32 v[116:117], v[116:117], v[164:165] op_sel_hi:[1,0]
	v_pk_mul_f32 v[166:167], v[114:115], v[164:165] op_sel_hi:[1,0]
	v_pk_mul_f32 v[164:165], v[112:113], v[164:165] op_sel_hi:[1,0]
	v_cvt_pk_bf16_f32 v112, v124, v125
	v_cvt_pk_bf16_f32 v113, v126, v127
	v_cvt_pk_bf16_f32 v114, v120, v121
	v_cvt_pk_bf16_f32 v115, v122, v123
	global_store_dwordx4 v[160:161], v[112:115], off
	s_nop 1
	v_cvt_pk_bf16_f32 v112, v116, v117
	v_cvt_pk_bf16_f32 v113, v118, v119
	v_cvt_pk_bf16_f32 v114, v164, v165
	v_cvt_pk_bf16_f32 v115, v166, v167
	v_lshl_add_u64 v[206:207], v[160:161], 0, s[98:99]
	global_store_dwordx4 v[206:207], v[112:115], off
	global_load_dwordx4 v[112:115], v[162:163], off
	s_waitcnt vmcnt(0)
	v_mov_b32_e32 v116, v113
	v_mov_b32_e32 v117, v114
	v_mov_b32_e32 v113, v115
	v_pk_add_f32 v[112:113], v[116:117], v[112:113]
	v_lshlrev_b64 v[114:115], 8, v[158:159]
	v_add_f32_e32 v112, v112, v113
	ds_bpermute_b32 v113, v155, v112
	v_lshl_add_u64 v[114:115], s[12:13], 0, v[114:115]
	v_lshl_add_u64 v[114:115], v[114:115], 0, v[142:143]
	s_waitcnt lgkmcnt(0)
	v_add_f32_e32 v116, v112, v113
	ds_bpermute_b32 v117, v156, v116
	v_or_b32_e32 v112, 32, v144
	v_ashrrev_i32_e32 v113, 31, v112
	s_waitcnt lgkmcnt(0)
	v_add_f32_e32 v116, v116, v117
	v_fmamk_f32 v116, v116, 0x3b800000, v153
	v_mov_b32_e32 v118, v116
	v_lshlrev_b64 v[116:117], 6, v[112:113]
	v_lshl_add_u64 v[116:117], v[128:129], 0, v[116:117]
	v_rsq_f32_e32 v123, v118
	v_mul_f32_e32 v122, 0.5, v118
	v_mul_f32_e32 v118, v123, v123
	v_fma_f32 v122, -v122, v118, 0.5
	v_fma_f32 v118, v123, v122, v123
	v_pk_mul_f32 v[110:111], v[110:111], v[118:119] op_sel_hi:[1,0]
	v_pk_mul_f32 v[108:109], v[108:109], v[118:119] op_sel_hi:[1,0]
	v_pk_mul_f32 v[106:107], v[106:107], v[118:119] op_sel_hi:[1,0]
	v_pk_mul_f32 v[104:105], v[104:105], v[118:119] op_sel_hi:[1,0]
	v_pk_mul_f32 v[102:103], v[102:103], v[118:119] op_sel_hi:[1,0]
	v_pk_mul_f32 v[100:101], v[100:101], v[118:119] op_sel_hi:[1,0]
	v_pk_mul_f32 v[120:121], v[98:99], v[118:119] op_sel_hi:[1,0]
	v_pk_mul_f32 v[118:119], v[96:97], v[118:119] op_sel_hi:[1,0]
	v_cvt_pk_bf16_f32 v96, v108, v109
	v_cvt_pk_bf16_f32 v97, v110, v111
	v_cvt_pk_bf16_f32 v98, v104, v105
	v_cvt_pk_bf16_f32 v99, v106, v107
	global_store_dwordx4 v[114:115], v[96:99], off
	s_nop 1
	v_cvt_pk_bf16_f32 v96, v100, v101
	v_cvt_pk_bf16_f32 v97, v102, v103
	v_cvt_pk_bf16_f32 v98, v118, v119
	v_cvt_pk_bf16_f32 v99, v120, v121
	v_lshl_add_u64 v[206:207], v[114:115], 0, s[98:99]
	global_store_dwordx4 v[206:207], v[96:99], off
	global_load_dwordx4 v[96:99], v[116:117], off
	s_waitcnt vmcnt(0)
	v_mov_b32_e32 v100, v97
	v_mov_b32_e32 v101, v98
	v_mov_b32_e32 v97, v99
	v_pk_add_f32 v[96:97], v[100:101], v[96:97]
	v_lshlrev_b64 v[98:99], 8, v[112:113]
	v_add_f32_e32 v96, v96, v97
	ds_bpermute_b32 v97, v155, v96
	v_lshl_add_u64 v[98:99], s[12:13], 0, v[98:99]
	v_lshl_add_u64 v[98:99], v[98:99], 0, v[142:143]
	s_waitcnt lgkmcnt(0)
	v_add_f32_e32 v100, v96, v97
	ds_bpermute_b32 v101, v156, v100
	v_or_b32_e32 v96, 48, v144
	v_ashrrev_i32_e32 v97, 31, v96
	s_waitcnt lgkmcnt(0)
	v_add_f32_e32 v100, v100, v101
	v_fmamk_f32 v100, v100, 0x3b800000, v153
	v_mov_b32_e32 v102, v100
	v_lshlrev_b64 v[100:101], 6, v[96:97]
	v_lshl_add_u64 v[100:101], v[128:129], 0, v[100:101]
	v_rsq_f32_e32 v107, v102
	v_mul_f32_e32 v106, 0.5, v102
	v_mul_f32_e32 v102, v107, v107
	v_fma_f32 v106, -v106, v102, 0.5
	v_fma_f32 v102, v107, v106, v107
	v_pk_mul_f32 v[94:95], v[94:95], v[102:103] op_sel_hi:[1,0]
	v_pk_mul_f32 v[92:93], v[92:93], v[102:103] op_sel_hi:[1,0]
	v_pk_mul_f32 v[90:91], v[90:91], v[102:103] op_sel_hi:[1,0]
	v_pk_mul_f32 v[88:89], v[88:89], v[102:103] op_sel_hi:[1,0]
	v_pk_mul_f32 v[86:87], v[86:87], v[102:103] op_sel_hi:[1,0]
	v_pk_mul_f32 v[84:85], v[84:85], v[102:103] op_sel_hi:[1,0]
	v_pk_mul_f32 v[104:105], v[82:83], v[102:103] op_sel_hi:[1,0]
	v_pk_mul_f32 v[102:103], v[80:81], v[102:103] op_sel_hi:[1,0]
	v_cvt_pk_bf16_f32 v80, v92, v93
	v_cvt_pk_bf16_f32 v81, v94, v95
	v_cvt_pk_bf16_f32 v82, v88, v89
	v_cvt_pk_bf16_f32 v83, v90, v91
	global_store_dwordx4 v[98:99], v[80:83], off
	s_nop 1
	v_cvt_pk_bf16_f32 v80, v84, v85
	v_cvt_pk_bf16_f32 v81, v86, v87
	v_cvt_pk_bf16_f32 v82, v102, v103
	v_cvt_pk_bf16_f32 v83, v104, v105
	v_lshl_add_u64 v[206:207], v[98:99], 0, s[98:99]
	global_store_dwordx4 v[206:207], v[80:83], off
	global_load_dwordx4 v[80:83], v[100:101], off
	s_waitcnt vmcnt(0)
	v_mov_b32_e32 v84, v81
	v_mov_b32_e32 v85, v82
	v_mov_b32_e32 v81, v83
	v_pk_add_f32 v[80:81], v[84:85], v[80:81]
	v_lshlrev_b64 v[82:83], 8, v[96:97]
	v_add_f32_e32 v80, v80, v81
	ds_bpermute_b32 v81, v155, v80
	v_lshl_add_u64 v[82:83], s[12:13], 0, v[82:83]
	v_lshl_add_u64 v[82:83], v[82:83], 0, v[142:143]
	s_waitcnt lgkmcnt(0)
	v_add_f32_e32 v84, v80, v81
	ds_bpermute_b32 v85, v156, v84
	v_add_u32_e32 v80, 0x80, v144
	v_ashrrev_i32_e32 v81, 31, v80
	s_waitcnt lgkmcnt(0)
	v_add_f32_e32 v84, v84, v85
	v_fmamk_f32 v84, v84, 0x3b800000, v153
	v_mov_b32_e32 v86, v84
	v_lshlrev_b64 v[84:85], 6, v[80:81]
	v_lshl_add_u64 v[84:85], v[128:129], 0, v[84:85]
	v_rsq_f32_e32 v91, v86
	v_mul_f32_e32 v90, 0.5, v86
	v_mul_f32_e32 v86, v91, v91
	v_fma_f32 v90, -v90, v86, 0.5
	v_fma_f32 v86, v91, v90, v91
	v_pk_mul_f32 v[78:79], v[78:79], v[86:87] op_sel_hi:[1,0]
	v_pk_mul_f32 v[76:77], v[76:77], v[86:87] op_sel_hi:[1,0]
	v_pk_mul_f32 v[74:75], v[74:75], v[86:87] op_sel_hi:[1,0]
	v_pk_mul_f32 v[72:73], v[72:73], v[86:87] op_sel_hi:[1,0]
	v_pk_mul_f32 v[70:71], v[70:71], v[86:87] op_sel_hi:[1,0]
	v_pk_mul_f32 v[68:69], v[68:69], v[86:87] op_sel_hi:[1,0]
	v_pk_mul_f32 v[88:89], v[66:67], v[86:87] op_sel_hi:[1,0]
	v_pk_mul_f32 v[86:87], v[64:65], v[86:87] op_sel_hi:[1,0]
	v_cvt_pk_bf16_f32 v64, v76, v77
	v_cvt_pk_bf16_f32 v65, v78, v79
	v_cvt_pk_bf16_f32 v66, v72, v73
	v_cvt_pk_bf16_f32 v67, v74, v75
	global_store_dwordx4 v[82:83], v[64:67], off
	s_nop 1
	v_cvt_pk_bf16_f32 v64, v68, v69
	v_cvt_pk_bf16_f32 v65, v70, v71
	v_cvt_pk_bf16_f32 v66, v86, v87
	v_cvt_pk_bf16_f32 v67, v88, v89
	v_lshl_add_u64 v[206:207], v[82:83], 0, s[98:99]
	global_store_dwordx4 v[206:207], v[64:67], off
	global_load_dwordx4 v[64:67], v[84:85], off
	s_waitcnt vmcnt(0)
	v_mov_b32_e32 v68, v65
	v_mov_b32_e32 v69, v66
	v_mov_b32_e32 v65, v67
	v_pk_add_f32 v[64:65], v[68:69], v[64:65]
	v_lshlrev_b64 v[66:67], 8, v[80:81]
	v_add_f32_e32 v64, v64, v65
	ds_bpermute_b32 v65, v155, v64
	v_lshl_add_u64 v[66:67], s[12:13], 0, v[66:67]
	v_lshl_add_u64 v[66:67], v[66:67], 0, v[142:143]
	s_waitcnt lgkmcnt(0)
	v_add_f32_e32 v68, v64, v65
	ds_bpermute_b32 v69, v156, v68
	v_add_u32_e32 v64, 0x90, v144
	v_ashrrev_i32_e32 v65, 31, v64
	s_waitcnt lgkmcnt(0)
	v_add_f32_e32 v68, v68, v69
	v_fmamk_f32 v68, v68, 0x3b800000, v153
	v_mov_b32_e32 v70, v68
	v_lshlrev_b64 v[68:69], 6, v[64:65]
	v_lshl_add_u64 v[68:69], v[128:129], 0, v[68:69]
	v_rsq_f32_e32 v75, v70
	v_mul_f32_e32 v74, 0.5, v70
	v_mul_f32_e32 v70, v75, v75
	v_fma_f32 v74, -v74, v70, 0.5
	v_fma_f32 v70, v75, v74, v75
	v_pk_mul_f32 v[62:63], v[62:63], v[70:71] op_sel_hi:[1,0]
	v_pk_mul_f32 v[60:61], v[60:61], v[70:71] op_sel_hi:[1,0]
	v_pk_mul_f32 v[58:59], v[58:59], v[70:71] op_sel_hi:[1,0]
	v_pk_mul_f32 v[56:57], v[56:57], v[70:71] op_sel_hi:[1,0]
	v_pk_mul_f32 v[54:55], v[54:55], v[70:71] op_sel_hi:[1,0]
	v_pk_mul_f32 v[52:53], v[52:53], v[70:71] op_sel_hi:[1,0]
	v_pk_mul_f32 v[72:73], v[50:51], v[70:71] op_sel_hi:[1,0]
	v_pk_mul_f32 v[70:71], v[48:49], v[70:71] op_sel_hi:[1,0]
	v_cvt_pk_bf16_f32 v48, v60, v61
	v_cvt_pk_bf16_f32 v49, v62, v63
	v_cvt_pk_bf16_f32 v50, v56, v57
	v_cvt_pk_bf16_f32 v51, v58, v59
	global_store_dwordx4 v[66:67], v[48:51], off
	s_nop 1
	v_cvt_pk_bf16_f32 v48, v52, v53
	v_cvt_pk_bf16_f32 v49, v54, v55
	v_cvt_pk_bf16_f32 v50, v70, v71
	v_cvt_pk_bf16_f32 v51, v72, v73
	v_lshl_add_u64 v[206:207], v[66:67], 0, s[98:99]
	global_store_dwordx4 v[206:207], v[48:51], off
	global_load_dwordx4 v[48:51], v[68:69], off
	s_waitcnt vmcnt(0)
	v_mov_b32_e32 v52, v49
	v_mov_b32_e32 v53, v50
	v_mov_b32_e32 v49, v51
	v_pk_add_f32 v[48:49], v[52:53], v[48:49]
	v_lshlrev_b64 v[50:51], 8, v[64:65]
	v_add_f32_e32 v48, v48, v49
	ds_bpermute_b32 v49, v155, v48
	v_lshl_add_u64 v[50:51], s[12:13], 0, v[50:51]
	v_lshl_add_u64 v[50:51], v[50:51], 0, v[142:143]
	s_waitcnt lgkmcnt(0)
	v_add_f32_e32 v52, v48, v49
	ds_bpermute_b32 v53, v156, v52
	v_add_u32_e32 v48, 0xa0, v144
	v_ashrrev_i32_e32 v49, 31, v48
	s_waitcnt lgkmcnt(0)
	v_add_f32_e32 v52, v52, v53
	v_fmamk_f32 v52, v52, 0x3b800000, v153
	v_mov_b32_e32 v54, v52
	v_lshlrev_b64 v[52:53], 6, v[48:49]
	v_lshl_add_u64 v[52:53], v[128:129], 0, v[52:53]
	v_rsq_f32_e32 v59, v54
	v_mul_f32_e32 v58, 0.5, v54
	v_mul_f32_e32 v54, v59, v59
	v_fma_f32 v58, -v58, v54, 0.5
	v_fma_f32 v54, v59, v58, v59
	v_pk_mul_f32 v[46:47], v[46:47], v[54:55] op_sel_hi:[1,0]
	v_pk_mul_f32 v[44:45], v[44:45], v[54:55] op_sel_hi:[1,0]
	v_pk_mul_f32 v[42:43], v[42:43], v[54:55] op_sel_hi:[1,0]
	v_pk_mul_f32 v[40:41], v[40:41], v[54:55] op_sel_hi:[1,0]
	v_pk_mul_f32 v[38:39], v[38:39], v[54:55] op_sel_hi:[1,0]
	v_pk_mul_f32 v[36:37], v[36:37], v[54:55] op_sel_hi:[1,0]
	v_pk_mul_f32 v[56:57], v[34:35], v[54:55] op_sel_hi:[1,0]
	v_pk_mul_f32 v[54:55], v[32:33], v[54:55] op_sel_hi:[1,0]
	v_cvt_pk_bf16_f32 v32, v44, v45
	v_cvt_pk_bf16_f32 v33, v46, v47
	v_cvt_pk_bf16_f32 v34, v40, v41
	v_cvt_pk_bf16_f32 v35, v42, v43
	global_store_dwordx4 v[50:51], v[32:35], off
	s_nop 1
	v_cvt_pk_bf16_f32 v32, v36, v37
	v_cvt_pk_bf16_f32 v33, v38, v39
	v_cvt_pk_bf16_f32 v34, v54, v55
	v_cvt_pk_bf16_f32 v35, v56, v57
	v_lshl_add_u64 v[206:207], v[50:51], 0, s[98:99]
	global_store_dwordx4 v[206:207], v[32:35], off
	global_load_dwordx4 v[32:35], v[52:53], off
	s_waitcnt vmcnt(0)
	v_mov_b32_e32 v36, v33
	v_mov_b32_e32 v37, v34
	v_mov_b32_e32 v33, v35
	v_pk_add_f32 v[32:33], v[36:37], v[32:33]
	v_lshlrev_b64 v[34:35], 8, v[48:49]
	v_add_f32_e32 v32, v32, v33
	ds_bpermute_b32 v33, v155, v32
	v_lshl_add_u64 v[34:35], s[12:13], 0, v[34:35]
	v_lshl_add_u64 v[34:35], v[34:35], 0, v[142:143]
	s_waitcnt lgkmcnt(0)
	v_add_f32_e32 v36, v32, v33
	ds_bpermute_b32 v37, v156, v36
	v_add_u32_e32 v32, 0xb0, v144
	v_ashrrev_i32_e32 v33, 31, v32
	s_waitcnt lgkmcnt(0)
	v_add_f32_e32 v36, v36, v37
	v_fmamk_f32 v36, v36, 0x3b800000, v153
	v_mov_b32_e32 v38, v36
	v_lshlrev_b64 v[36:37], 6, v[32:33]
	v_lshl_add_u64 v[36:37], v[128:129], 0, v[36:37]
	v_rsq_f32_e32 v43, v38
	v_mul_f32_e32 v42, 0.5, v38
	v_mul_f32_e32 v38, v43, v43
	v_fma_f32 v42, -v42, v38, 0.5
	v_fma_f32 v38, v43, v42, v43
	v_pk_mul_f32 v[30:31], v[30:31], v[38:39] op_sel_hi:[1,0]
	v_pk_mul_f32 v[28:29], v[28:29], v[38:39] op_sel_hi:[1,0]
	v_pk_mul_f32 v[26:27], v[26:27], v[38:39] op_sel_hi:[1,0]
	v_pk_mul_f32 v[24:25], v[24:25], v[38:39] op_sel_hi:[1,0]
	v_pk_mul_f32 v[22:23], v[22:23], v[38:39] op_sel_hi:[1,0]
	v_pk_mul_f32 v[20:21], v[20:21], v[38:39] op_sel_hi:[1,0]
	v_pk_mul_f32 v[40:41], v[18:19], v[38:39] op_sel_hi:[1,0]
	v_pk_mul_f32 v[38:39], v[16:17], v[38:39] op_sel_hi:[1,0]
	v_cvt_pk_bf16_f32 v16, v28, v29
	v_cvt_pk_bf16_f32 v17, v30, v31
	v_cvt_pk_bf16_f32 v18, v24, v25
	v_cvt_pk_bf16_f32 v19, v26, v27
	global_store_dwordx4 v[34:35], v[16:19], off
	s_nop 1
	v_cvt_pk_bf16_f32 v16, v20, v21
	v_cvt_pk_bf16_f32 v17, v22, v23
	v_cvt_pk_bf16_f32 v18, v38, v39
	v_cvt_pk_bf16_f32 v19, v40, v41
	v_lshl_add_u64 v[206:207], v[34:35], 0, s[98:99]
	global_store_dwordx4 v[206:207], v[16:19], off
	global_load_dwordx4 v[16:19], v[36:37], off
	s_waitcnt vmcnt(0)
	v_mov_b32_e32 v20, v17
	v_mov_b32_e32 v21, v18
	v_mov_b32_e32 v17, v19
	v_pk_add_f32 v[16:17], v[20:21], v[16:17]
	s_nop 0
	v_add_f32_e32 v16, v16, v17
	ds_bpermute_b32 v17, v155, v16
	s_waitcnt lgkmcnt(0)
	v_add_f32_e32 v16, v16, v17
	ds_bpermute_b32 v17, v156, v16
	s_waitcnt lgkmcnt(0)
	v_add_f32_e32 v16, v16, v17
	v_fmamk_f32 v16, v16, 0x3b800000, v153
	v_mov_b32_e32 v18, v16
	v_lshlrev_b64 v[16:17], 8, v[32:33]
	v_lshl_add_u64 v[16:17], s[12:13], 0, v[16:17]
	v_lshl_add_u64 v[16:17], v[16:17], 0, v[142:143]
	v_rsq_f32_e32 v23, v18
	v_mul_f32_e32 v22, 0.5, v18
	v_mul_f32_e32 v18, v23, v23
	v_fma_f32 v22, -v22, v18, 0.5
	v_fma_f32 v18, v23, v22, v23
	s_andn2_b64 vcc, exec, s[0:1]
	v_pk_mul_f32 v[14:15], v[14:15], v[18:19] op_sel_hi:[1,0]
	v_pk_mul_f32 v[12:13], v[12:13], v[18:19] op_sel_hi:[1,0]
	v_pk_mul_f32 v[10:11], v[10:11], v[18:19] op_sel_hi:[1,0]
	v_pk_mul_f32 v[8:9], v[8:9], v[18:19] op_sel_hi:[1,0]
	v_pk_mul_f32 v[6:7], v[6:7], v[18:19] op_sel_hi:[1,0]
	v_pk_mul_f32 v[4:5], v[4:5], v[18:19] op_sel_hi:[1,0]
	v_pk_mul_f32 v[20:21], v[2:3], v[18:19] op_sel_hi:[1,0]
	v_pk_mul_f32 v[18:19], v[0:1], v[18:19] op_sel_hi:[1,0]
	v_cvt_pk_bf16_f32 v0, v12, v13
	v_cvt_pk_bf16_f32 v1, v14, v15
	v_cvt_pk_bf16_f32 v2, v8, v9
	v_cvt_pk_bf16_f32 v3, v10, v11
	s_mov_b64 s[0:1], -1
	global_store_dwordx4 v[16:17], v[0:3], off
	s_nop 1
	v_cvt_pk_bf16_f32 v0, v4, v5
	v_cvt_pk_bf16_f32 v1, v6, v7
	v_cvt_pk_bf16_f32 v2, v18, v19
	v_cvt_pk_bf16_f32 v3, v20, v21
	v_lshl_add_u64 v[206:207], v[16:17], 0, s[98:99]
	global_store_dwordx4 v[206:207], v[0:3], off
	s_cbranch_vccnz .LBB0_448
	s_andn2_b64 vcc, exec, s[10:11]
	s_cbranch_vccnz .LBB0_447
	s_barrier
	s_branch .LBB0_447

.LBB0_513:
	s_cmp_lt_i32 s58, 5
	s_cselect_b64 s[4:5], -1, 0
	s_add_u32 s10, s56, 0x8200000
	s_addc_u32 s11, s57, 0
	s_and_b64 s[4:5], s[4:5], s[0:1]
	v_readlane_b32 s0, v254, 0
	s_cmpk_lt_i32 s0, 0x800
	s_cselect_b64 s[70:71], -1, 0
	s_and_b64 s[0:1], s[4:5], s[70:71]
	s_andn2_b64 vcc, exec, s[0:1]
	v_and_b32_e32 v191, 31, v192
	v_lshrrev_b32_e32 v201, 5, v190
	v_lshlrev_b32_e32 v203, 3, v192
	v_lshlrev_b32_e32 v205, 1, v192
	v_cmp_gt_u32_e64 s[0:1], 32, v190
	v_lshrrev_b32_e32 v199, 3, v190
	v_lshrrev_b32_e32 v193, 2, v190
	s_cbranch_vccnz .LBB0_615
	v_writelane_b32 v254, s4, 38
	v_mov_b32_e32 v1, 0
	v_lshlrev_b32_e32 v0, 6, v190
	s_cmp_lg_u32 0, -1
	v_writelane_b32 v254, s5, 39
	v_lshl_add_u64 v[196:197], s[78:79], 0, v[0:1]
	v_lshlrev_b32_e32 v0, 8, v192
	v_lshlrev_b32_e32 v4, 4, v192
	s_cselect_b32 s4, 0, 0
	s_waitcnt lgkmcnt(0)
	v_and_b32_e32 v3, 0x3c00, v0
	v_and_b32_e32 v0, 32, v205
	v_and_b32_e32 v4, 0xc0, v4
	v_lshlrev_b32_e32 v7, 10, v201
	v_lshlrev_b32_e32 v8, 4, v191
	s_add_i32 s5, s4, 0xc000
	s_add_i32 s4, s4, 0x8000
	v_and_b32_e32 v2, 24, v203
	v_lshl_or_b32 v5, v201, 8, v4
	v_add_u32_e32 v9, 0, v0
	v_add3_u32 v207, 0, v7, v8
	v_add_u32_e32 v7, s5, v0
	v_add_u32_e32 v0, s4, v0
	v_writelane_b32 v254, s70, 46
	v_add3_u32 v237, v0, v2, v5
	v_and_b32_e32 v0, 3, v192
	v_writelane_b32 v254, s71, 47
	v_lshlrev_b32_e32 v0, 4, v0
	v_writelane_b32 v254, s96, 42
	v_lshlrev_b32_e32 v194, 8, v190
	v_mov_b32_e32 v195, v1
	v_lshl_add_u64 v[12:13], s[56:57], 0, v[0:1]
	s_mov_b64 s[4:5], 0x18204080
	v_writelane_b32 v254, s97, 43
	v_lshl_add_u64 v[208:209], v[12:13], 0, s[4:5]
	v_lshl_add_u64 v[14:15], s[56:57], 0, v[194:195]
	s_mov_b64 s[4:5], 0x18204000
	v_lshlrev_b32_e32 v0, 8, v190
	v_writelane_b32 v254, s94, 44
	v_add3_u32 v231, v7, v2, v5
	v_or_b32_e32 v7, 8, v199
	v_lshl_add_u64 v[210:211], v[14:15], 0, s[4:5]
	v_lshl_add_u64 v[14:15], s[56:57], 0, v[0:1]
	v_mbcnt_lo_u32_b32 v0, -1, 0
	v_writelane_b32 v254, s95, 45
	v_mul_u32_u24_e32 v6, 0x300, v191
	v_lshlrev_b32_e32 v4, 3, v201
	v_lshlrev_b32_e32 v234, 7, v7
	v_lshlrev_b32_e32 v202, 10, v7
	v_or_b32_e32 v7, 16, v199
	s_mov_b64 s[4:5], 0x10204000
	v_mbcnt_hi_u32_b32 v242, -1, v0
	v_or_b32_e32 v6, v4, v6
	v_add3_u32 v228, v9, v2, v5
	v_lshlrev_b32_e32 v235, 7, v7
	v_lshlrev_b32_e32 v204, 10, v7
	v_or_b32_e32 v7, 24, v199
	v_lshlrev_b32_e32 v8, 7, v190
	v_lshl_or_b32 v10, v191, 9, v4
	v_readlane_b32 s77, v254, 0
	v_lshl_add_u64 v[212:213], v[14:15], 0, s[4:5]
	s_mov_b64 s[4:5], 0x10a04000
	v_and_b32_e32 v0, 64, v242
	s_mov_b32 s73, 0
	v_add_u32_e32 v229, 0x9000, v228
	v_lshlrev_b32_e32 v230, 4, v201
	v_lshlrev_b32_e32 v232, 9, v201
	v_and_b32_e32 v198, 56, v203
	v_lshlrev_b32_e32 v233, 7, v199
	v_lshlrev_b32_e32 v200, 10, v199
	v_lshlrev_b32_e32 v236, 7, v7
	v_lshlrev_b32_e32 v206, 10, v7
	s_lshl_b32 s23, s77, 4
	s_lshl_b32 s25, s60, 4
	v_lshl_add_u64 v[214:215], v[12:13], 0, s[4:5]
	v_lshlrev_b32_e32 v238, 7, v193
	v_lshrrev_b32_e32 v239, 2, v3
	s_mov_b64 s[20:21], 0x4000
	v_lshlrev_b32_e32 v240, 1, v6
	v_lshlrev_b32_e32 v216, 1, v4
	s_mov_b32 s22, 0x3fc90fda
	s_mov_b32 s24, 0x33a22168
	s_mov_b32 s26, 0x27c234c5
	s_mov_b32 s76, 0x394ca1f9
	s_mov_b32 s78, 0xbe2aaaa3
	s_mov_b32 s80, 0x37ccf5ce
	s_mov_b32 s82, 0x3d2aaaa5
	s_mov_b64 s[90:91], 0x8000
	s_mov_b64 s[92:93], 0x2000
	s_mov_b64 s[94:95], 0x4000
	s_mov_b64 s[96:97], 0x10000
	s_mov_b32 s27, 0x41000000
	v_lshlrev_b32_e32 v218, 1, v8
	v_lshlrev_b32_e32 v241, 1, v10
	s_mov_b64 s[14:15], 0x8000
	s_mov_b64 s[62:63], 0xc000
	s_mov_b64 s[64:65], 0x10000
	s_mov_b64 s[66:67], 0x1ec000
	s_mov_b64 s[68:69], 0x1f8000
	v_lshlrev_b32_e32 v220, 1, v2
	v_xor_b32_e32 v243, 32, v242
	v_add_u32_e32 v244, 64, v0
	s_branch .LBB0_517

.LBB0_519:
	s_and_b32 s4, s81, 7
	s_lshl_b32 s7, s75, 21
	s_lshl_b32 s34, s4, 23
	s_mul_i32 s4, s79, 0x600
	s_add_u32 s4, s8, s4
	s_addc_u32 s5, s9, 0
	s_mul_i32 s6, s74, 0xc0
	s_add_u32 s38, s4, s6
	s_addc_u32 s39, s5, 0
	s_lshl_b32 s4, s83, 8
	s_add_u32 s4, s12, s4
	s_addc_u32 s5, s13, 0
	s_lshl_b32 s6, s74, 23
	s_add_u32 s40, s4, s6
	v_readfirstlane_b32 s6, v192
	s_addc_u32 s41, s5, 0
	s_lshr_b32 s30, s6, 6
	s_lshl_b32 s42, s83, 6
	s_lshl_b32 s72, s30, 5
	s_mul_i32 s4, s30, 0xc000
	s_mul_hi_u32 s5, s72, 0x600
	s_add_u32 s4, s38, s4
	s_addc_u32 s5, s39, s5
	v_lshl_add_u64 v[2:3], s[40:41], 0, v[194:195]
	s_lshl_b32 s18, s30, 4
	s_mov_b32 s19, s73
	s_mov_b32 s43, s73
	s_and_b32 s35, s6, 0x3fffffc0
	v_lshl_add_u64 v[182:183], v[2:3], 0, s[18:19]
	s_bfe_u32 s19, s6, 0x20006
	s_lshr_b32 s6, s6, 2
	v_lshl_add_u64 v[2:3], v[196:197], 0, s[42:43]
	s_lshl_b32 s42, s19, 4
	s_and_b32 s70, s6, 0x3fffffc0
	s_lshl_b32 s85, s30, 10
	v_lshl_or_b32 v0, s19, 12, v239
	s_cmp_lg_u32 0, -1
	v_lshl_add_u64 v[226:227], v[2:3], 0, s[42:43]
	v_lshl_add_u64 v[2:3], s[40:41], 0, v[0:1]
	s_mov_b32 s71, s73
	s_cselect_b32 s6, 0, 0
	s_lshl_b32 s86, s19, 10
	v_lshl_add_u64 v[2:3], v[2:3], 0, s[70:71]
	v_mov_b32_e32 v221, v1
	s_add_i32 s87, s85, s6
	s_mov_b32 m0, s87
	s_nop 0
	global_load_lds_dwordx4 v[182:183], off
	s_bitset1_b32 s86, 13
	v_lshl_add_u64 v[10:11], v[2:3], 0, v[220:221]
	s_mov_b64 s[40:41], 0x80
	s_add_i32 s84, s86, s6
	s_mov_b32 m0, s84
	s_nop 0
	global_load_lds_dwordx4 v[226:227], off
	v_lshl_add_u64 v[222:223], v[10:11], 0, s[40:41]
	s_add_i32 s71, s87, 0x9000
	s_mov_b32 m0, s71
	s_nop 0
	global_load_lds_dwordx4 v[222:223], off
	s_add_i32 s19, s6, 0x3000
	v_lshl_add_u64 v[2:3], v[182:183], 0, s[20:21]
	s_add_i32 s37, s85, s19
	s_mov_b32 m0, s37
	s_nop 0
	global_load_lds_dwordx4 v[2:3], off
	s_mov_b64 s[40:41], 0x1000
	v_lshl_add_u64 v[2:3], v[226:227], 0, s[40:41]
	s_add_i32 s19, s86, s19
	s_mov_b32 m0, s19
	s_nop 0
	global_load_lds_dwordx4 v[2:3], off
	v_or_b32_e32 v4, s72, v191
	v_mov_b64_e32 v[2:3], s[38:39]
	s_movk_i32 s19, 0x600
	v_mad_u64_u32 v[2:3], s[38:39], v4, s19, v[2:3]
	v_mov_b32_e32 v217, v1
	v_lshl_add_u64 v[2:3], v[2:3], 0, v[216:217]
	global_load_dwordx4 v[6:9], v[2:3], off offset:128
	v_or_b32_e32 v4, s36, v191
	v_add_u32_e32 v4, s72, v4
	v_lshrrev_b32_e32 v5, 6, v4
	v_cvt_f32_u32_e32 v16, v5
	v_cmp_lt_i32_e32 vcc, v243, v244
	v_and_b32_e32 v29, 63, v4
	s_mov_b32 s36, 0x3c08839e
	v_cndmask_b32_e32 v5, v242, v243, vcc
	v_mul_f32_e32 v17, 0x3ea1e89b, v16
	v_lshlrev_b32_e32 v28, 2, v5
	v_mul_f32_e32 v4, 0x3f22f983, v16
	v_mul_f32_e32 v5, 0x3f22f983, v17
	v_rndne_f32_e32 v4, v4
	v_rndne_f32_e32 v5, v5
	v_pk_fma_f32 v[18:19], v[4:5], s[22:23], v[16:17] op_sel_hi:[1,0,1] neg_lo:[1,0,0] neg_hi:[1,0,0]
	v_mov_b64_e32 v[12:13], s[36:37]
	v_pk_fma_f32 v[18:19], v[4:5], s[24:25], v[18:19] op_sel_hi:[1,0,1] neg_lo:[1,0,0] neg_hi:[1,0,0]
	s_mov_b32 s36, 0xbab6061a
	v_pk_fma_f32 v[18:19], v[4:5], s[26:27], v[18:19] op_sel_hi:[1,0,1] neg_lo:[1,0,0] neg_hi:[1,0,0]
	v_mov_b64_e32 v[14:15], s[36:37]
	v_pk_mul_f32 v[20:21], v[18:19], v[18:19]
	v_cvt_i32_f32_e32 v30, v4
	v_pk_fma_f32 v[24:25], v[20:21], s[76:77], v[12:13] op_sel_hi:[1,0,0] neg_lo:[1,0,0] neg_hi:[1,0,0]
	v_cvt_i32_f32_e32 v17, v5
	v_pk_mul_f32 v[22:23], v[18:19], v[20:21]
	v_pk_fma_f32 v[26:27], v[20:21], s[80:81], v[14:15] op_sel_hi:[1,0,0]
	v_pk_fma_f32 v[24:25], v[20:21], v[24:25], s[78:79] op_sel_hi:[1,1,0]
	global_load_dwordx4 v[110:113], v240, s[4:5]
	global_load_dwordx4 v[106:109], v240, s[4:5] offset:32
	global_load_dwordx4 v[102:105], v240, s[4:5] offset:64
	global_load_dwordx4 v[98:101], v240, s[4:5] offset:96
	v_pk_fma_f32 v[18:19], v[22:23], v[24:25], v[18:19]
	v_pk_fma_f32 v[22:23], v[20:21], v[26:27], s[82:83] op_sel_hi:[1,1,0]
	global_load_dwordx4 v[2:5], v[2:3], off offset:160
	v_pk_fma_f32 v[22:23], v[20:21], v[22:23], -0.5 op_sel_hi:[1,1,0]
	v_and_b32_e32 v25, 2, v30
	v_pk_fma_f32 v[20:21], v[20:21], v[22:23], 1.0 op_sel_hi:[1,1,0]
	v_and_b32_e32 v23, 1, v30
	v_and_b32_e32 v22, 1, v17
	v_cmp_eq_u32_e32 vcc, 0, v23
	v_cmp_eq_u32_e64 s[4:5], 0, v22
	s_mov_b32 s36, 0x3dcccccd
	v_cndmask_b32_e32 v23, v20, v18, vcc
	v_cndmask_b32_e32 v20, v18, v20, vcc
	v_and_b32_e32 v18, 2, v17
	v_cndmask_b32_e64 v22, v21, v19, s[4:5]
	v_cmp_eq_u32_e32 vcc, 0, v18
	v_add_u32_e32 v17, 1, v17
	v_cndmask_b32_e64 v21, v19, v21, s[4:5]
	v_cndmask_b32_e64 v19, -v22, v22, vcc
	v_cmp_eq_u32_e32 vcc, 0, v25
	v_add_u32_e32 v22, 1, v30
	v_and_b32_e32 v17, 2, v17
	v_cndmask_b32_e64 v18, -v23, v23, vcc
	v_and_b32_e32 v22, 2, v22
	v_cmp_eq_u32_e32 vcc, 0, v17
	s_mov_b32 s37, 0x3d0186e3
	s_mov_b32 s38, 0x3c23d70b
	v_cndmask_b32_e64 v21, -v21, v21, vcc
	v_cmp_eq_u32_e32 vcc, 0, v22
	s_mov_b32 s39, 0x3b4f3e39
	s_mov_b32 s40, 0x3a831270
	v_cndmask_b32_e64 v20, -v20, v20, vcc
	s_mov_b32 s41, 0x39a5cb61
	s_addk_i32 s6, 0x6000
	s_or_b32 s7, s7, s34
	s_mov_b32 s88, -1
	s_movk_i32 s89, 0x6000
	v_lshl_add_u64 v[178:179], v[226:227], 0, s[94:95]
	v_lshl_add_u64 v[180:181], v[182:183], 0, s[96:97]
	s_waitcnt vmcnt(5)
	ds_bpermute_b32 v24, v28, v6
	v_and_b32_e32 v23, 0xffff0000, v6
	v_lshlrev_b32_e32 v22, 16, v6
	ds_bpermute_b32 v31, v28, v7
	ds_bpermute_b32 v32, v28, v8
	s_waitcnt lgkmcnt(2)
	v_and_b32_e32 v25, 0xffff0000, v24
	v_lshlrev_b32_e32 v24, 16, v24
	v_pk_mul_f32 v[18:19], v[18:19], v[24:25]
	ds_bpermute_b32 v33, v28, v9
	v_cndmask_b32_e64 v19, v19, -v19, s[0:1]
	v_cndmask_b32_e64 v18, v18, -v18, s[0:1]
	v_pk_fma_f32 v[18:19], v[20:21], v[22:23], v[18:19]
	v_pk_mul_f32 v[20:21], v[16:17], s[36:37] op_sel_hi:[0,1]
	v_mul_f32_e32 v6, 0x3f22f983, v20
	v_rndne_f32_e32 v22, v6
	v_mul_f32_e32 v6, 0x3f22f983, v21
	v_rndne_f32_e32 v23, v6
	v_pk_fma_f32 v[20:21], v[22:23], s[22:23], v[20:21] op_sel_hi:[1,0,1] neg_lo:[1,0,0] neg_hi:[1,0,0]
	v_cvt_i32_f32_e32 v6, v23
	v_pk_fma_f32 v[20:21], v[22:23], s[24:25], v[20:21] op_sel_hi:[1,0,1] neg_lo:[1,0,0] neg_hi:[1,0,0]
	v_cvt_i32_f32_e32 v17, v22
	v_pk_fma_f32 v[20:21], v[22:23], s[26:27], v[20:21] op_sel_hi:[1,0,1] neg_lo:[1,0,0] neg_hi:[1,0,0]
	v_cvt_pk_bf16_f32 v114, v18, v19
	v_pk_mul_f32 v[24:25], v[20:21], v[20:21]
	s_waitcnt vmcnt(0)
	ds_bpermute_b32 v40, v28, v4
	v_pk_fma_f32 v[26:27], v[24:25], s[76:77], v[12:13] op_sel_hi:[1,0,0] neg_lo:[1,0,0] neg_hi:[1,0,0]
	v_pk_mul_f32 v[22:23], v[20:21], v[24:25]
	v_pk_fma_f32 v[26:27], v[24:25], v[26:27], s[78:79] op_sel_hi:[1,1,0]
	ds_bpermute_b32 v62, v28, v5
	v_pk_fma_f32 v[20:21], v[22:23], v[26:27], v[20:21]
	v_pk_fma_f32 v[22:23], v[24:25], s[80:81], v[14:15] op_sel_hi:[1,0,0]
	v_and_b32_e32 v26, 2, v17
	v_pk_fma_f32 v[22:23], v[24:25], v[22:23], s[82:83] op_sel_hi:[1,1,0]
	s_nop 0
	v_pk_fma_f32 v[22:23], v[24:25], v[22:23], -0.5 op_sel_hi:[1,1,0]
	s_nop 0
	v_pk_fma_f32 v[22:23], v[24:25], v[22:23], 1.0 op_sel_hi:[1,1,0]
	v_and_b32_e32 v25, 1, v17
	v_and_b32_e32 v24, 1, v6
	v_cmp_eq_u32_e32 vcc, 0, v25
	v_cmp_eq_u32_e64 s[4:5], 0, v24
	v_add_u32_e32 v17, 1, v17
	v_cndmask_b32_e32 v25, v22, v20, vcc
	v_cndmask_b32_e32 v22, v20, v22, vcc
	v_and_b32_e32 v20, 2, v6
	v_cndmask_b32_e64 v24, v23, v21, s[4:5]
	v_cmp_eq_u32_e32 vcc, 0, v20
	v_add_u32_e32 v6, 1, v6
	v_cndmask_b32_e64 v23, v21, v23, s[4:5]
	v_cndmask_b32_e64 v21, -v24, v24, vcc
	v_cmp_eq_u32_e32 vcc, 0, v26
	v_and_b32_e32 v6, 2, v6
	v_and_b32_e32 v17, 2, v17
	v_cndmask_b32_e64 v20, -v25, v25, vcc
	v_cmp_eq_u32_e32 vcc, 0, v6
	v_and_b32_e32 v25, 0xffff0000, v7
	v_lshlrev_b32_e32 v24, 16, v7
	s_waitcnt lgkmcnt(4)
	v_and_b32_e32 v7, 0xffff0000, v31
	v_lshlrev_b32_e32 v6, 16, v31
	v_cndmask_b32_e64 v23, -v23, v23, vcc
	v_cmp_eq_u32_e32 vcc, 0, v17
	v_pk_mul_f32 v[6:7], v[20:21], v[6:7]
	v_pk_mul_f32 v[20:21], v[16:17], s[38:39] op_sel_hi:[0,1]
	v_cndmask_b32_e64 v22, -v22, v22, vcc
	v_cndmask_b32_e64 v7, v7, -v7, s[0:1]
	v_cndmask_b32_e64 v6, v6, -v6, s[0:1]
	v_mul_f32_e32 v17, 0x3f22f983, v20
	v_pk_fma_f32 v[6:7], v[22:23], v[24:25], v[6:7]
	v_rndne_f32_e32 v22, v17
	v_mul_f32_e32 v17, 0x3f22f983, v21
	v_rndne_f32_e32 v23, v17
	v_pk_fma_f32 v[20:21], v[22:23], s[22:23], v[20:21] op_sel_hi:[1,0,1] neg_lo:[1,0,0] neg_hi:[1,0,0]
	v_cvt_i32_f32_e32 v17, v23
	v_pk_fma_f32 v[20:21], v[22:23], s[24:25], v[20:21] op_sel_hi:[1,0,1] neg_lo:[1,0,0] neg_hi:[1,0,0]
	v_cvt_i32_f32_e32 v30, v22
	v_pk_fma_f32 v[20:21], v[22:23], s[26:27], v[20:21] op_sel_hi:[1,0,1] neg_lo:[1,0,0] neg_hi:[1,0,0]
	v_cvt_pk_bf16_f32 v115, v6, v7
	v_pk_mul_f32 v[24:25], v[20:21], v[20:21]
	s_nop 0
	v_pk_fma_f32 v[26:27], v[24:25], s[76:77], v[12:13] op_sel_hi:[1,0,0] neg_lo:[1,0,0] neg_hi:[1,0,0]
	v_pk_mul_f32 v[22:23], v[20:21], v[24:25]
	v_pk_fma_f32 v[26:27], v[24:25], v[26:27], s[78:79] op_sel_hi:[1,1,0]
	s_nop 0
	v_pk_fma_f32 v[20:21], v[22:23], v[26:27], v[20:21]
	v_pk_fma_f32 v[22:23], v[24:25], s[80:81], v[14:15] op_sel_hi:[1,0,0]
	v_and_b32_e32 v26, 2, v30
	v_pk_fma_f32 v[22:23], v[24:25], v[22:23], s[82:83] op_sel_hi:[1,1,0]
	s_waitcnt lgkmcnt(3)
	v_and_b32_e32 v27, 0xffff0000, v32
	v_pk_fma_f32 v[22:23], v[24:25], v[22:23], -0.5 op_sel_hi:[1,1,0]
	s_nop 0
	v_pk_fma_f32 v[22:23], v[24:25], v[22:23], 1.0 op_sel_hi:[1,1,0]
	v_and_b32_e32 v25, 1, v30
	v_and_b32_e32 v24, 1, v17
	v_cmp_eq_u32_e32 vcc, 0, v25
	v_cmp_eq_u32_e64 s[4:5], 0, v24
	s_nop 0
	v_cndmask_b32_e32 v25, v22, v20, vcc
	v_cndmask_b32_e32 v22, v20, v22, vcc
	v_and_b32_e32 v20, 2, v17
	v_cndmask_b32_e64 v24, v23, v21, s[4:5]
	v_cmp_eq_u32_e32 vcc, 0, v20
	v_add_u32_e32 v17, 1, v17
	v_cndmask_b32_e64 v23, v21, v23, s[4:5]
	v_cndmask_b32_e64 v21, -v24, v24, vcc
	v_cmp_eq_u32_e32 vcc, 0, v26
	v_add_u32_e32 v24, 1, v30
	v_and_b32_e32 v17, 2, v17
	v_cndmask_b32_e64 v20, -v25, v25, vcc
	v_and_b32_e32 v24, 2, v24
	v_cmp_eq_u32_e32 vcc, 0, v17
	v_lshlrev_b32_e32 v26, 16, v32
	v_pk_mul_f32 v[20:21], v[20:21], v[26:27]
	v_cndmask_b32_e64 v23, -v23, v23, vcc
	v_cmp_eq_u32_e32 vcc, 0, v24
	v_pk_mul_f32 v[16:17], v[16:17], s[40:41] op_sel_hi:[0,1]
	v_and_b32_e32 v25, 0xffff0000, v8
	v_cndmask_b32_e64 v22, -v22, v22, vcc
	v_lshlrev_b32_e32 v24, 16, v8
	v_cndmask_b32_e64 v21, v21, -v21, s[0:1]
	v_cndmask_b32_e64 v20, v20, -v20, s[0:1]
	v_mul_f32_e32 v8, 0x3f22f983, v16
	v_pk_fma_f32 v[20:21], v[22:23], v[24:25], v[20:21]
	v_rndne_f32_e32 v22, v8
	v_mul_f32_e32 v8, 0x3f22f983, v17
	v_rndne_f32_e32 v23, v8
	v_pk_fma_f32 v[16:17], v[22:23], s[22:23], v[16:17] op_sel_hi:[1,0,1] neg_lo:[1,0,0] neg_hi:[1,0,0]
	v_cvt_i32_f32_e32 v8, v23
	v_pk_fma_f32 v[16:17], v[22:23], s[24:25], v[16:17] op_sel_hi:[1,0,1] neg_lo:[1,0,0] neg_hi:[1,0,0]
	v_cvt_i32_f32_e32 v30, v22
	v_pk_fma_f32 v[16:17], v[22:23], s[26:27], v[16:17] op_sel_hi:[1,0,1] neg_lo:[1,0,0] neg_hi:[1,0,0]
	v_cvt_pk_bf16_f32 v116, v20, v21
	v_pk_mul_f32 v[24:25], v[16:17], v[16:17]
	s_nop 0
	v_pk_fma_f32 v[26:27], v[24:25], s[76:77], v[12:13] op_sel_hi:[1,0,0] neg_lo:[1,0,0] neg_hi:[1,0,0]
	v_pk_mul_f32 v[22:23], v[16:17], v[24:25]
	v_pk_fma_f32 v[26:27], v[24:25], v[26:27], s[78:79] op_sel_hi:[1,1,0]
	s_nop 0
	v_pk_fma_f32 v[16:17], v[22:23], v[26:27], v[16:17]
	v_pk_fma_f32 v[22:23], v[24:25], s[80:81], v[14:15] op_sel_hi:[1,0,0]
	v_and_b32_e32 v26, 2, v30
	v_pk_fma_f32 v[22:23], v[24:25], v[22:23], s[82:83] op_sel_hi:[1,1,0]
	s_nop 0
	v_pk_fma_f32 v[22:23], v[24:25], v[22:23], -0.5 op_sel_hi:[1,1,0]
	s_nop 0
	v_pk_fma_f32 v[22:23], v[24:25], v[22:23], 1.0 op_sel_hi:[1,1,0]
	v_and_b32_e32 v25, 1, v30
	v_and_b32_e32 v24, 1, v8
	v_cmp_eq_u32_e32 vcc, 0, v25
	v_cmp_eq_u32_e64 s[4:5], 0, v24
	s_nop 0
	v_cndmask_b32_e32 v25, v22, v16, vcc
	v_cndmask_b32_e32 v22, v16, v22, vcc
	v_and_b32_e32 v16, 2, v8
	v_cndmask_b32_e64 v24, v23, v17, s[4:5]
	v_cmp_eq_u32_e32 vcc, 0, v16
	v_add_u32_e32 v8, 1, v8
	v_cndmask_b32_e64 v23, v17, v23, s[4:5]
	v_cndmask_b32_e64 v17, -v24, v24, vcc
	v_cmp_eq_u32_e32 vcc, 0, v26
	v_add_u32_e32 v24, 1, v30
	v_and_b32_e32 v8, 2, v8
	v_cndmask_b32_e64 v16, -v25, v25, vcc
	v_and_b32_e32 v24, 2, v24
	v_cmp_eq_u32_e32 vcc, 0, v8
	v_and_b32_e32 v25, 0xffff0000, v9
	s_waitcnt lgkmcnt(2)
	v_lshlrev_b32_e32 v8, 16, v33
	v_cndmask_b32_e64 v23, -v23, v23, vcc
	v_cmp_eq_u32_e32 vcc, 0, v24
	v_lshlrev_b32_e32 v24, 16, v9
	v_and_b32_e32 v9, 0xffff0000, v33
	v_pk_mul_f32 v[8:9], v[16:17], v[8:9]
	v_cndmask_b32_e64 v22, -v22, v22, vcc
	v_cndmask_b32_e64 v9, v9, -v9, s[0:1]
	v_cndmask_b32_e64 v8, v8, -v8, s[0:1]
	v_pk_fma_f32 v[8:9], v[22:23], v[24:25], v[8:9]
	ds_bpermute_b32 v22, v28, v2
	v_cvt_pk_bf16_f32 v117, v8, v9
	v_cvt_f32_ubyte0_e32 v8, v29
	v_mul_f32_e32 v9, 0x3ea1e89b, v8
	v_mul_f32_e32 v6, 0x3f22f983, v8
	v_mul_f32_e32 v7, 0x3f22f983, v9
	v_rndne_f32_e32 v6, v6
	v_rndne_f32_e32 v7, v7
	v_pk_fma_f32 v[16:17], v[6:7], s[22:23], v[8:9] op_sel_hi:[1,0,1] neg_lo:[1,0,0] neg_hi:[1,0,0]
	v_cvt_i32_f32_e32 v9, v6
	v_pk_fma_f32 v[16:17], v[6:7], s[24:25], v[16:17] op_sel_hi:[1,0,1] neg_lo:[1,0,0] neg_hi:[1,0,0]
	v_cvt_i32_f32_e32 v23, v7
	v_pk_fma_f32 v[16:17], v[6:7], s[26:27], v[16:17] op_sel_hi:[1,0,1] neg_lo:[1,0,0] neg_hi:[1,0,0]
	ds_bpermute_b32 v24, v28, v3
	v_pk_mul_f32 v[18:19], v[16:17], v[16:17]
	s_nop 0
	v_pk_fma_f32 v[20:21], v[18:19], s[76:77], v[12:13] op_sel_hi:[1,0,0] neg_lo:[1,0,0] neg_hi:[1,0,0]
	v_pk_mul_f32 v[6:7], v[16:17], v[18:19]
	v_pk_fma_f32 v[20:21], v[18:19], v[20:21], s[78:79] op_sel_hi:[1,1,0]
	s_nop 0
	v_pk_fma_f32 v[6:7], v[6:7], v[20:21], v[16:17]
	v_pk_fma_f32 v[16:17], v[18:19], s[80:81], v[14:15] op_sel_hi:[1,0,0]
	v_and_b32_e32 v20, 2, v9
	v_pk_fma_f32 v[16:17], v[18:19], v[16:17], s[82:83] op_sel_hi:[1,1,0]
	s_waitcnt lgkmcnt(1)
	v_and_b32_e32 v21, 0xffff0000, v22
	v_pk_fma_f32 v[16:17], v[18:19], v[16:17], -0.5 op_sel_hi:[1,1,0]
	s_nop 0
	v_pk_fma_f32 v[16:17], v[18:19], v[16:17], 1.0 op_sel_hi:[1,1,0]
	v_and_b32_e32 v19, 1, v9
	v_and_b32_e32 v18, 1, v23
	v_cmp_eq_u32_e32 vcc, 0, v19
	v_cmp_eq_u32_e64 s[4:5], 0, v18
	v_add_u32_e32 v9, 1, v9
	v_cndmask_b32_e32 v19, v16, v6, vcc
	v_cndmask_b32_e32 v16, v6, v16, vcc
	v_and_b32_e32 v6, 2, v23
	v_cndmask_b32_e64 v18, v17, v7, s[4:5]
	v_cmp_eq_u32_e32 vcc, 0, v6
	v_cndmask_b32_e64 v17, v7, v17, s[4:5]
	v_and_b32_e32 v9, 2, v9
	v_cndmask_b32_e64 v7, -v18, v18, vcc
	v_add_u32_e32 v18, 1, v23
	v_cmp_eq_u32_e32 vcc, 0, v20
	v_and_b32_e32 v18, 2, v18
	v_lshlrev_b32_e32 v20, 16, v22
	v_cndmask_b32_e64 v6, -v19, v19, vcc
	v_cmp_eq_u32_e32 vcc, 0, v18
	v_pk_mul_f32 v[6:7], v[6:7], v[20:21]
	v_and_b32_e32 v19, 0xffff0000, v2
	v_cndmask_b32_e64 v17, -v17, v17, vcc
	v_cmp_eq_u32_e32 vcc, 0, v9
	v_lshlrev_b32_e32 v18, 16, v2
	v_cndmask_b32_e64 v7, v7, -v7, s[0:1]
	v_cndmask_b32_e64 v16, -v16, v16, vcc
	v_cndmask_b32_e64 v6, v6, -v6, s[0:1]
	v_pk_fma_f32 v[6:7], v[16:17], v[18:19], v[6:7]
	v_pk_mul_f32 v[16:17], v[8:9], s[36:37] op_sel_hi:[0,1]
	v_mul_f32_e32 v2, 0x3f22f983, v16
	v_rndne_f32_e32 v18, v2
	v_mul_f32_e32 v2, 0x3f22f983, v17
	v_rndne_f32_e32 v19, v2
	v_pk_fma_f32 v[16:17], v[18:19], s[22:23], v[16:17] op_sel_hi:[1,0,1] neg_lo:[1,0,0] neg_hi:[1,0,0]
	v_cvt_i32_f32_e32 v2, v19
	v_pk_fma_f32 v[16:17], v[18:19], s[24:25], v[16:17] op_sel_hi:[1,0,1] neg_lo:[1,0,0] neg_hi:[1,0,0]
	v_cvt_i32_f32_e32 v9, v18
	v_pk_fma_f32 v[16:17], v[18:19], s[26:27], v[16:17] op_sel_hi:[1,0,1] neg_lo:[1,0,0] neg_hi:[1,0,0]
	v_cvt_pk_bf16_f32 v126, v6, v7
	v_pk_mul_f32 v[20:21], v[16:17], v[16:17]
	s_mov_b32 s36, 0
	v_pk_fma_f32 v[22:23], v[20:21], s[76:77], v[12:13] op_sel_hi:[1,0,0] neg_lo:[1,0,0] neg_hi:[1,0,0]
	v_pk_mul_f32 v[18:19], v[16:17], v[20:21]
	v_pk_fma_f32 v[22:23], v[20:21], v[22:23], s[78:79] op_sel_hi:[1,1,0]
	s_mov_b32 s37, s36
	v_pk_fma_f32 v[16:17], v[18:19], v[22:23], v[16:17]
	v_pk_fma_f32 v[18:19], v[20:21], s[80:81], v[14:15] op_sel_hi:[1,0,0]
	v_and_b32_e32 v22, 2, v9
	v_pk_fma_f32 v[18:19], v[20:21], v[18:19], s[82:83] op_sel_hi:[1,1,0]
	s_mov_b32 s42, s36
	v_pk_fma_f32 v[18:19], v[20:21], v[18:19], -0.5 op_sel_hi:[1,1,0]
	s_mov_b32 s43, s36
	v_pk_fma_f32 v[18:19], v[20:21], v[18:19], 1.0 op_sel_hi:[1,1,0]
	v_and_b32_e32 v21, 1, v9
	v_and_b32_e32 v20, 1, v2
	v_cmp_eq_u32_e32 vcc, 0, v21
	v_cmp_eq_u32_e64 s[4:5], 0, v20
	v_add_u32_e32 v9, 1, v9
	v_cndmask_b32_e32 v21, v18, v16, vcc
	v_cndmask_b32_e32 v18, v16, v18, vcc
	v_and_b32_e32 v16, 2, v2
	v_cndmask_b32_e64 v20, v19, v17, s[4:5]
	v_cmp_eq_u32_e32 vcc, 0, v16
	v_add_u32_e32 v2, 1, v2
	v_cndmask_b32_e64 v19, v17, v19, s[4:5]
	v_cndmask_b32_e64 v17, -v20, v20, vcc
	v_cmp_eq_u32_e32 vcc, 0, v22
	v_and_b32_e32 v2, 2, v2
	v_and_b32_e32 v9, 2, v9
	v_cndmask_b32_e64 v16, -v21, v21, vcc
	v_cmp_eq_u32_e32 vcc, 0, v2
	v_and_b32_e32 v21, 0xffff0000, v3
	v_lshlrev_b32_e32 v20, 16, v3
	s_waitcnt lgkmcnt(0)
	v_and_b32_e32 v3, 0xffff0000, v24
	v_lshlrev_b32_e32 v2, 16, v24
	v_cndmask_b32_e64 v19, -v19, v19, vcc
	v_cmp_eq_u32_e32 vcc, 0, v9
	v_pk_mul_f32 v[2:3], v[16:17], v[2:3]
	v_pk_mul_f32 v[16:17], v[8:9], s[38:39] op_sel_hi:[0,1]
	v_cndmask_b32_e64 v18, -v18, v18, vcc
	v_cndmask_b32_e64 v3, v3, -v3, s[0:1]
	v_cndmask_b32_e64 v2, v2, -v2, s[0:1]
	v_mul_f32_e32 v9, 0x3f22f983, v16
	v_pk_fma_f32 v[2:3], v[18:19], v[20:21], v[2:3]
	v_rndne_f32_e32 v18, v9
	v_mul_f32_e32 v9, 0x3f22f983, v17
	v_rndne_f32_e32 v19, v9
	v_pk_fma_f32 v[16:17], v[18:19], s[22:23], v[16:17] op_sel_hi:[1,0,1] neg_lo:[1,0,0] neg_hi:[1,0,0]
	v_cvt_i32_f32_e32 v9, v19
	v_pk_fma_f32 v[16:17], v[18:19], s[24:25], v[16:17] op_sel_hi:[1,0,1] neg_lo:[1,0,0] neg_hi:[1,0,0]
	v_cvt_i32_f32_e32 v24, v18
	v_pk_fma_f32 v[16:17], v[18:19], s[26:27], v[16:17] op_sel_hi:[1,0,1] neg_lo:[1,0,0] neg_hi:[1,0,0]
	v_cvt_pk_bf16_f32 v127, v2, v3
	v_pk_mul_f32 v[20:21], v[16:17], v[16:17]
	s_mov_b32 s38, s36
	v_pk_fma_f32 v[22:23], v[20:21], s[76:77], v[12:13] op_sel_hi:[1,0,0] neg_lo:[1,0,0] neg_hi:[1,0,0]
	v_pk_mul_f32 v[18:19], v[16:17], v[20:21]
	v_pk_fma_f32 v[22:23], v[20:21], v[22:23], s[78:79] op_sel_hi:[1,1,0]
	s_mov_b32 s39, s36
	v_pk_fma_f32 v[16:17], v[18:19], v[22:23], v[16:17]
	v_pk_fma_f32 v[18:19], v[20:21], s[80:81], v[14:15] op_sel_hi:[1,0,0]
	v_and_b32_e32 v23, 2, v24
	v_pk_fma_f32 v[18:19], v[20:21], v[18:19], s[82:83] op_sel_hi:[1,1,0]
	s_mov_b32 s44, s36
	v_pk_fma_f32 v[18:19], v[20:21], v[18:19], -0.5 op_sel_hi:[1,1,0]
	s_mov_b32 s45, s36
	v_pk_fma_f32 v[18:19], v[20:21], v[18:19], 1.0 op_sel_hi:[1,1,0]
	v_and_b32_e32 v21, 1, v24
	v_and_b32_e32 v20, 1, v9
	v_cmp_eq_u32_e32 vcc, 0, v21
	v_cmp_eq_u32_e64 s[4:5], 0, v20
	s_mov_b32 s46, s36
	v_cndmask_b32_e32 v21, v18, v16, vcc
	v_cndmask_b32_e32 v41, v16, v18, vcc
	v_and_b32_e32 v16, 2, v9
	v_cndmask_b32_e64 v20, v19, v17, s[4:5]
	v_cndmask_b32_e64 v22, v17, v19, s[4:5]
	v_cmp_eq_u32_e32 vcc, 0, v16
	v_lshl_add_u64 v[16:17], v[182:183], 0, s[90:91]
	s_add_i32 s4, s85, s6
	s_mov_b32 m0, s4
	s_nop 0
	global_load_lds_dwordx4 v[16:17], off
	v_lshl_add_u64 v[16:17], v[226:227], 0, s[92:93]
	s_add_i32 s4, s86, s6
	s_mov_b32 m0, s4
	s_nop 0
	global_load_lds_dwordx4 v[16:17], off
	s_waitcnt vmcnt(3) lgkmcnt(0)
	s_barrier
	ds_read_b128 v[16:19], v207
	ds_read_b128 v[34:37], v207 offset:512
	v_add_u32_e32 v9, 1, v9
	v_cndmask_b32_e64 v39, -v20, v20, vcc
	v_cmp_eq_u32_e32 vcc, 0, v23
	v_add_u32_e32 v20, 1, v24
	v_and_b32_e32 v9, 2, v9
	v_cndmask_b32_e64 v38, -v21, v21, vcc
	v_and_b32_e32 v42, 2, v20
	v_cmp_eq_u32_e32 vcc, 0, v9
	ds_read_b128 v[50:53], v207 offset:2048
	v_pk_mul_f32 v[8:9], v[8:9], s[40:41] op_sel_hi:[0,1]
	v_cndmask_b32_e64 v55, -v22, v22, vcc
	v_cmp_eq_u32_e32 vcc, 0, v42
	s_waitcnt lgkmcnt(2)
	v_mfma_f32_32x32x16_bf16 v[18:33], v[16:19], v[110:113], 0
	v_and_b32_e32 v17, 0xffff0000, v4
	v_cndmask_b32_e64 v54, -v41, v41, vcc
	v_and_b32_e32 v41, 0xffff0000, v40
	v_lshlrev_b32_e32 v40, 16, v40
	v_mul_f32_e64 v56, v38, v40
	v_mul_f32_e64 v57, v39, v41
	v_lshlrev_b32_e32 v16, 16, v4
	v_cndmask_b32_e64 v57, v57, -v57, s[0:1]
	v_cndmask_b32_e64 v56, v56, -v56, s[0:1]
	v_pk_fma_f32 v[16:17], v[54:55], v[16:17], v[56:57]
	ds_read_b128 v[54:57], v207 offset:2560
	s_waitcnt lgkmcnt(2)
	v_mfma_f32_32x32x16_bf16 v[34:49], v[34:37], v[110:113], 0
	v_mul_f32_e32 v4, 0x3f22f983, v8
	v_rndne_f32_e32 v58, v4
	v_mul_f32_e32 v4, 0x3f22f983, v9
	v_rndne_f32_e32 v59, v4
	v_fma_f32 v8, -v58, s22, v8
	v_fma_f32 v9, -v59, s22, v9
	v_cvt_i32_f32_e32 v4, v59
	v_pk_fma_f32 v[8:9], v[58:59], s[24:25], v[8:9] op_sel_hi:[1,0,1] neg_lo:[1,0,0] neg_hi:[1,0,0]
	s_waitcnt lgkmcnt(1)
	v_mfma_f32_32x32x16_bf16 v[18:33], v[50:53], v[106:109], v[18:33]
	v_fma_f32 v8, -v58, s26, v8
	v_fma_f32 v9, -v59, s26, v9
	ds_read_b128 v[50:53], v207 offset:4096
	v_mul_f32_e64 v60, v8, v8
	v_mul_f32_e64 v61, v9, v9
	v_cvt_i32_f32_e32 v58, v58
	v_pk_fma_f32 v[12:13], v[60:61], s[76:77], v[12:13] op_sel_hi:[1,0,0] neg_lo:[1,0,0] neg_hi:[1,0,0]
	v_cvt_pk_bf16_f32 v128, v16, v17
	v_pk_fma_f32 v[12:13], v[60:61], v[12:13], s[78:79] op_sel_hi:[1,1,0]
	s_waitcnt lgkmcnt(1)
	v_mfma_f32_32x32x16_bf16 v[34:49], v[54:57], v[106:109], v[34:49]
	v_mul_f32_e64 v54, v8, v60
	v_mul_f32_e64 v55, v9, v61
	s_mov_b32 s40, s36
	v_fma_f32 v8, v54, v12, v8
	v_fma_f32 v9, v55, v13, v9
	ds_read_b128 v[54:57], v207 offset:4608
	v_pk_fma_f32 v[12:13], v[60:61], s[80:81], v[14:15] op_sel_hi:[1,0,0]
	s_mov_b32 s41, s36
	v_pk_fma_f32 v[12:13], v[60:61], v[12:13], s[82:83] op_sel_hi:[1,1,0]
	s_waitcnt lgkmcnt(1)
	v_mfma_f32_32x32x16_bf16 v[18:33], v[50:53], v[102:105], v[18:33]
	v_fma_f32 v12, v60, v12, -0.5
	v_fma_f32 v13, v61, v13, -0.5
	v_and_b32_e32 v52, 1, v4
	v_and_b32_e32 v53, 1, v58
	v_fma_f32 v50, v60, v12, 1.0
	v_fma_f32 v51, v61, v13, 1.0
	ds_read_b128 v[12:15], v207 offset:6144
	v_cmp_eq_u32_e32 vcc, 0, v53
	v_cmp_eq_u32_e64 s[4:5], 0, v52
	s_waitcnt lgkmcnt(1)
	v_mfma_f32_32x32x16_bf16 v[34:49], v[54:57], v[102:105], v[34:49]
	v_cndmask_b32_e32 v54, v50, v8, vcc
	v_cndmask_b32_e64 v55, v51, v9, s[4:5]
	v_cndmask_b32_e32 v56, v8, v50, vcc
	v_cndmask_b32_e64 v57, v9, v51, s[4:5]
	ds_read_b128 v[50:53], v207 offset:6656
	v_and_b32_e32 v8, 2, v4
	v_cmp_eq_u32_e32 vcc, 0, v8
	s_waitcnt lgkmcnt(1)
	v_mfma_f32_32x32x16_bf16 v[18:33], v[12:15], v[98:101], v[18:33]
	v_and_b32_e32 v12, 2, v58
	v_cndmask_b32_e64 v9, -v55, v55, vcc
	v_cmp_eq_u32_e32 vcc, 0, v12
	ds_read_b128 v[12:15], v207 offset:8192
	v_add_u32_e32 v4, 1, v4
	v_cndmask_b32_e64 v8, -v54, v54, vcc
	v_and_b32_e32 v4, 2, v4
	s_waitcnt lgkmcnt(1)
	v_mfma_f32_32x32x16_bf16 v[34:49], v[50:53], v[98:101], v[34:49]
	v_add_u32_e32 v50, 1, v58
	v_and_b32_e32 v54, 2, v50
	ds_read_b128 v[50:53], v207 offset:8704
	v_cmp_eq_u32_e32 vcc, 0, v4
	v_lshlrev_b32_e32 v4, 16, v62
	s_mov_b64 s[4:5], 0xc000
	v_cndmask_b32_e64 v55, -v57, v57, vcc
	v_cmp_eq_u32_e32 vcc, 0, v54
	v_and_b32_e32 v57, 0xffff0000, v5
	s_waitcnt lgkmcnt(1)
	v_mfma_f32_32x32x16_bf16 v[18:33], v[12:15], v[114:117], v[18:33]
	v_cndmask_b32_e64 v54, -v56, v56, vcc
	v_lshlrev_b32_e32 v56, 16, v5
	v_and_b32_e32 v5, 0xffff0000, v62
	v_mul_f32_e64 v4, v8, v4
	v_mul_f32_e64 v5, v9, v5
	ds_read_b128 v[12:15], v207 offset:10240
	v_cndmask_b32_e64 v5, v5, -v5, s[0:1]
	v_cndmask_b32_e64 v4, v4, -v4, s[0:1]
	v_pk_fma_f32 v[4:5], v[54:55], v[56:57], v[4:5]
	s_waitcnt lgkmcnt(1)
	v_mfma_f32_32x32x16_bf16 v[34:49], v[50:53], v[114:117], v[34:49]
	v_cvt_pk_bf16_f32 v129, v4, v5
	ds_read_b128 v[2:5], v207 offset:10752
	s_mov_b32 s47, s36
	s_mov_b32 s48, s36
	s_mov_b32 s49, s36
	s_mov_b32 s50, s36
	s_mov_b32 s51, s36
	s_waitcnt lgkmcnt(1)
	v_mfma_f32_32x32x16_bf16 v[18:33], v[12:15], v[126:129], v[18:33]
	s_movk_i32 s6, 0x3000
	s_waitcnt lgkmcnt(0)
	v_mfma_f32_32x32x16_bf16 v[34:49], v[2:5], v[126:129], v[34:49]
	s_nop 15
	s_nop 7
	s_waitcnt vmcnt(0) lgkmcnt(0)
	s_barrier
	v_lshl_add_u64 v[2:3], v[182:183], 0, s[4:5]
	v_max3_f32 v50, v18, v19, v34
	s_mov_b32 m0, s87
	s_nop 0
	global_load_lds_dwordx4 v[2:3], off
	v_max3_f32 v51, v20, v21, v35
	s_mov_b64 s[4:5], 0x4080
	v_max3_f32 v50, v50, v36, v37
	v_max3_f32 v51, v51, v24, v25
	v_lshl_add_u64 v[2:3], v[10:11], 0, s[4:5]
	v_max3_f32 v50, v50, v22, v23
	s_add_i32 s4, s87, 0xc000
	s_mov_b32 m0, s4
	s_nop 0
	global_load_lds_dwordx4 v[2:3], off
	v_max3_f32 v50, v50, v38, v39
	v_max3_f32 v51, v51, v40, v41
	ds_read_b128 v[66:69], v207 offset:12288
	ds_read_b128 v[82:85], v207 offset:12800
	ds_read_b128 v[158:161], v207 offset:14336
	ds_read_b128 v[154:157], v207 offset:14848
	ds_read_b128 v[150:153], v207 offset:16384
	ds_read_b128 v[146:149], v207 offset:16896
	ds_read_b128 v[142:145], v207 offset:18432
	ds_read_b128 v[138:141], v207 offset:18944
	v_max3_f32 v50, v50, v26, v27
	v_max3_f32 v51, v51, v28, v29
	v_mov_b64_e32 v[2:3], s[36:37]
	v_max3_f32 v50, v50, v42, v43
	v_max3_f32 v51, v51, v44, v45
	s_lshl_b32 s4, s35, 2
	v_max3_f32 v50, v50, v30, v31
	v_max3_f32 v51, v51, v32, v33
	v_mov_b64_e32 v[4:5], s[38:39]
	v_max3_f32 v50, v50, v46, v47
	v_max3_f32 v51, v51, v48, v49
	v_mov_b64_e32 v[6:7], s[40:41]
	v_mov_b64_e32 v[8:9], s[42:43]
	v_mov_b64_e32 v[10:11], s[44:45]
	v_mov_b64_e32 v[12:13], s[46:47]
	v_mov_b64_e32 v[14:15], s[48:49]
	v_mov_b64_e32 v[16:17], s[50:51]
	v_max_f32_e32 v50, v50, v51
	s_add_i32 s37, s4, 0
	v_mov_b32_e32 v51, v50
	s_nop 1
	v_permlane32_swap_b32_e32 v50, v51
	s_add_i32 s37, s37, 0x12000
	v_max_f32_e32 v50, v50, v51
	s_add_u32 s4, s7, s70
	v_sub_f32_e32 v34, v34, v50
	v_sub_f32_e32 v35, v35, v50
	v_sub_f32_e32 v36, v36, v50
	v_sub_f32_e32 v37, v37, v50
	v_sub_f32_e32 v38, v38, v50
	v_sub_f32_e32 v39, v39, v50
	v_sub_f32_e32 v40, v40, v50
	v_sub_f32_e32 v41, v41, v50
	v_sub_f32_e32 v42, v42, v50
	v_sub_f32_e32 v43, v43, v50
	v_sub_f32_e32 v44, v44, v50
	v_sub_f32_e32 v45, v45, v50
	v_sub_f32_e32 v46, v46, v50
	v_sub_f32_e32 v47, v47, v50
	v_sub_f32_e32 v48, v48, v50
	v_sub_f32_e32 v49, v49, v50
	v_add_f32_e32 v224, v1, v50
	v_sub_f32_e32 v18, v18, v50
	v_sub_f32_e32 v19, v19, v50
	v_sub_f32_e32 v20, v20, v50
	v_sub_f32_e32 v21, v21, v50
	v_sub_f32_e32 v22, v22, v50
	v_sub_f32_e32 v23, v23, v50
	v_sub_f32_e32 v24, v24, v50
	v_sub_f32_e32 v25, v25, v50
	v_sub_f32_e32 v26, v26, v50
	v_sub_f32_e32 v27, v27, v50
	v_sub_f32_e32 v28, v28, v50
	v_sub_f32_e32 v29, v29, v50
	v_sub_f32_e32 v30, v30, v50
	v_sub_f32_e32 v31, v31, v50
	v_sub_f32_e32 v32, v32, v50
	v_sub_f32_e32 v33, v33, v50
	s_nop 0
	v_exp_f32_e32 v50, v18
	v_exp_f32_e32 v51, v19
	v_exp_f32_e32 v52, v20
	v_exp_f32_e32 v53, v21
	v_exp_f32_e32 v54, v22
	v_exp_f32_e32 v55, v23
	v_exp_f32_e32 v56, v24
	v_exp_f32_e32 v57, v25
	v_exp_f32_e32 v58, v26
	v_exp_f32_e32 v59, v27
	v_exp_f32_e32 v60, v28
	v_exp_f32_e32 v61, v29
	v_exp_f32_e32 v62, v30
	v_exp_f32_e32 v63, v31
	v_exp_f32_e32 v64, v32
	v_exp_f32_e32 v65, v33
	v_exp_f32_e32 v34, v34
	v_exp_f32_e32 v35, v35
	v_exp_f32_e32 v36, v36
	v_exp_f32_e32 v37, v37
	v_exp_f32_e32 v38, v38
	v_exp_f32_e32 v39, v39
	v_exp_f32_e32 v40, v40
	v_exp_f32_e32 v41, v41
	v_exp_f32_e32 v42, v42
	v_exp_f32_e32 v43, v43
	v_exp_f32_e32 v44, v44
	v_exp_f32_e32 v45, v45
	v_exp_f32_e32 v46, v46
	v_exp_f32_e32 v47, v47
	v_exp_f32_e32 v48, v48
	v_exp_f32_e32 v49, v49
	s_addc_u32 s5, 0, 0
	s_waitcnt vmcnt(2) lgkmcnt(0)
	s_barrier
	v_lshl_add_u64 v[18:19], s[4:5], 0, v[0:1]
	s_add_u32 s4, s7, s18
	v_lshl_add_u64 v[184:185], v[208:209], 0, v[18:19]
	s_addc_u32 s5, 0, 0
	v_mov_b64_e32 v[32:33], v[16:17]
	s_mov_b64 s[40:41], 0x1fc000
	s_mov_b64 s[38:39], 0x1f8000
	v_lshl_add_u32 v217, v191, 2, s37
	v_lshl_add_u64 v[186:187], v[210:211], 0, s[4:5]
	v_mov_b32_e32 v0, 0
	v_mov_b64_e32 v[30:31], v[14:15]
	v_mov_b64_e32 v[28:29], v[12:13]
	v_mov_b64_e32 v[26:27], v[10:11]
	v_mov_b64_e32 v[24:25], v[8:9]
	v_mov_b64_e32 v[22:23], v[6:7]
	v_mov_b64_e32 v[20:21], v[4:5]
	v_mov_b64_e32 v[18:19], v[2:3]

.LBB0_534:
	s_mov_b64 s[4:5], 0x7d000
	s_cmp_lg_u32 0, -1
	v_lshl_add_u64 v[70:71], v[226:227], 0, s[4:5]
	s_cselect_b32 s4, 0, 0
	s_add_i32 s5, s4, s86
	s_addk_i32 s5, 0x6000
	s_mov_b32 m0, s5
	s_nop 0
	global_load_lds_dwordx4 v[70:71], off
	ds_read_b64_tr_b16 v[170:171], v228 offset:61440
	ds_read_b64_tr_b16 v[172:173], v228 offset:61952
	v_add_f32_e32 v70, v50, v51
	v_add_f32_e32 v70, v52, v70
	v_add_f32_e32 v70, v53, v70
	v_add_f32_e32 v70, v54, v70
	v_add_f32_e32 v86, v55, v70
	v_cvt_pk_bf16_f32 v134, v50, v51
	v_cvt_pk_bf16_f32 v135, v52, v53
	s_waitcnt lgkmcnt(9)
	v_mfma_f32_32x32x16_bf16 v[66:81], v[66:69], v[110:113], 0
	ds_read_b64_tr_b16 v[166:167], v229 offset:28672
	ds_read_b64_tr_b16 v[168:169], v229 offset:29184
	v_add_f32_e32 v50, v56, v86
	v_add_f32_e32 v50, v57, v50
	v_add_f32_e32 v50, v58, v50
	v_add_f32_e32 v50, v59, v50
	v_cvt_pk_bf16_f32 v136, v54, v55
	v_cvt_pk_bf16_f32 v137, v56, v57
	s_waitcnt lgkmcnt(10)
	v_mfma_f32_32x32x16_bf16 v[82:97], v[82:85], v[110:113], 0
	ds_read_b64_tr_b16 v[162:163], v228 offset:62464
	ds_read_b64_tr_b16 v[164:165], v228 offset:62976
	v_add_f32_e32 v50, v60, v50
	v_add_f32_e32 v50, v61, v50
	v_add_f32_e32 v50, v62, v50
	v_add_f32_e32 v50, v63, v50
	v_cvt_pk_bf16_f32 v130, v58, v59
	v_cvt_pk_bf16_f32 v131, v60, v61
	s_waitcnt lgkmcnt(11)
	v_mfma_f32_32x32x16_bf16 v[66:81], v[158:161], v[106:109], v[66:81]
	ds_read_b64_tr_b16 v[158:159], v229 offset:29696
	ds_read_b64_tr_b16 v[160:161], v229 offset:30208
	v_add_f32_e32 v50, v64, v50
	v_add_f32_e32 v50, v65, v50
	v_add_f32_e32 v50, v34, v50
	v_add_f32_e32 v50, v35, v50
	v_cvt_pk_bf16_f32 v132, v62, v63
	v_cvt_pk_bf16_f32 v133, v64, v65
	s_waitcnt lgkmcnt(12)
	v_mfma_f32_32x32x16_bf16 v[82:97], v[154:157], v[106:109], v[82:97]
	ds_read_b64_tr_b16 v[154:155], v228 offset:63488
	ds_read_b64_tr_b16 v[156:157], v228 offset:64000
	v_add_f32_e32 v50, v36, v50
	v_add_f32_e32 v50, v37, v50
	v_add_f32_e32 v50, v38, v50
	v_add_f32_e32 v50, v39, v50
	v_cvt_pk_bf16_f32 v122, v34, v35
	v_cvt_pk_bf16_f32 v123, v36, v37
	s_waitcnt lgkmcnt(13)
	v_mfma_f32_32x32x16_bf16 v[66:81], v[150:153], v[102:105], v[66:81]
	ds_read_b64_tr_b16 v[150:151], v229 offset:30720
	ds_read_b64_tr_b16 v[152:153], v229 offset:31232
	v_add_f32_e32 v34, v40, v50
	v_add_f32_e32 v34, v41, v34
	v_add_f32_e32 v34, v42, v34
	v_add_f32_e32 v34, v43, v34
	v_cvt_pk_bf16_f32 v124, v38, v39
	v_cvt_pk_bf16_f32 v125, v40, v41
	s_waitcnt lgkmcnt(14)
	v_mfma_f32_32x32x16_bf16 v[82:97], v[146:149], v[102:105], v[82:97]
	ds_read_b64_tr_b16 v[146:147], v228 offset:64512
	ds_read_b64_tr_b16 v[148:149], v228 offset:65024
	v_add_f32_e32 v34, v44, v34
	v_add_f32_e32 v34, v45, v34
	v_add_f32_e32 v34, v46, v34
	v_add_f32_e32 v34, v47, v34
	v_cvt_pk_bf16_f32 v118, v42, v43
	v_cvt_pk_bf16_f32 v119, v44, v45
	s_waitcnt lgkmcnt(14)
	v_mfma_f32_32x32x16_bf16 v[66:81], v[142:145], v[98:101], v[66:81]
	ds_read_b64_tr_b16 v[142:143], v229 offset:31744
	ds_read_b64_tr_b16 v[144:145], v229 offset:32256
	v_add_f32_e32 v34, v48, v34
	v_add_f32_e32 v34, v49, v34
	v_mfma_f32_32x32x16_bf16 v[82:97], v[138:141], v[98:101], v[82:97]
	v_add_f32_e32 v138, 0, v34
	v_cvt_pk_bf16_f32 v120, v46, v47
	v_cvt_pk_bf16_f32 v121, v48, v49
	ds_read_b128 v[34:37], v207 offset:8192
	v_add_f32_e32 v184, v0, v138
	s_waitcnt lgkmcnt(0)
	v_mfma_f32_32x32x16_bf16 v[66:81], v[34:37], v[114:117], v[66:81]
	ds_read_b128 v[34:37], v207 offset:8704
	s_waitcnt lgkmcnt(0)
	v_mfma_f32_32x32x16_bf16 v[82:97], v[34:37], v[114:117], v[82:97]
	ds_read_b128 v[34:37], v207 offset:10240
	s_waitcnt lgkmcnt(0)
	v_mfma_f32_32x32x16_bf16 v[66:81], v[34:37], v[126:129], v[66:81]
	ds_read_b128 v[34:37], v207 offset:10752
	s_waitcnt lgkmcnt(0)
	v_mfma_f32_32x32x16_bf16 v[82:97], v[34:37], v[126:129], v[82:97]
	s_nop 8
	v_add_f32_e64 v50, v66, -v224
	v_add_f32_e64 v51, v67, -v224
	v_add_f32_e64 v52, v68, -v224
	v_add_f32_e64 v53, v69, -v224
	v_add_f32_e64 v54, v70, -v224
	v_add_f32_e64 v55, v71, -v224
	v_pk_add_f32 v[56:57], v[72:73], v[224:225] op_sel_hi:[1,0] neg_lo:[0,1] neg_hi:[0,1]
	v_pk_add_f32 v[58:59], v[74:75], v[224:225] op_sel_hi:[1,0] neg_lo:[0,1] neg_hi:[0,1]
	v_pk_add_f32 v[60:61], v[76:77], v[224:225] op_sel_hi:[1,0] neg_lo:[0,1] neg_hi:[0,1]
	v_pk_add_f32 v[62:63], v[78:79], v[224:225] op_sel_hi:[1,0] neg_lo:[0,1] neg_hi:[0,1]
	v_pk_add_f32 v[34:35], v[82:83], v[224:225] op_sel_hi:[1,0] neg_lo:[0,1] neg_hi:[0,1]
	v_pk_add_f32 v[36:37], v[84:85], v[224:225] op_sel_hi:[1,0] neg_lo:[0,1] neg_hi:[0,1]
	v_pk_add_f32 v[38:39], v[86:87], v[224:225] op_sel_hi:[1,0] neg_lo:[0,1] neg_hi:[0,1]
	v_pk_add_f32 v[40:41], v[88:89], v[224:225] op_sel_hi:[1,0] neg_lo:[0,1] neg_hi:[0,1]
	v_pk_add_f32 v[42:43], v[90:91], v[224:225] op_sel_hi:[1,0] neg_lo:[0,1] neg_hi:[0,1]
	v_pk_add_f32 v[44:45], v[92:93], v[224:225] op_sel_hi:[1,0] neg_lo:[0,1] neg_hi:[0,1]
	v_pk_add_f32 v[46:47], v[94:95], v[224:225] op_sel_hi:[1,0] neg_lo:[0,1] neg_hi:[0,1]
	v_pk_add_f32 v[64:65], v[80:81], v[224:225] op_sel_hi:[1,0] neg_lo:[0,1] neg_hi:[0,1]
	v_pk_add_f32 v[48:49], v[96:97], v[224:225] op_sel_hi:[1,0] neg_lo:[0,1] neg_hi:[0,1]
	v_lshl_add_u64 v[66:67], v[182:183], 0, s[38:39]
	s_mov_b64 s[6:7], 0x1f0000
	s_mov_b32 m0, s87
	s_nop 0
	global_load_lds_dwordx4 v[66:67], off
	v_lshl_add_u64 v[66:67], v[222:223], 0, s[6:7]
	s_add_i32 s4, s4, s85
	v_max_f32_e32 v0, v50, v51
	s_add_i32 s36, s4, 0xc000
	s_mov_b32 m0, s36
	s_nop 0
	global_load_lds_dwordx4 v[66:67], off
	v_max3_f32 v66, v52, v53, v35
	v_max3_f32 v0, v0, v34, v36
	v_max3_f32 v0, v0, v37, v54
	v_max3_f32 v66, v66, v56, v57
	v_max3_f32 v0, v0, v55, v38
	v_max3_f32 v66, v66, v40, v41
	v_max3_f32 v0, v0, v39, v58
	v_max3_f32 v66, v66, v60, v61
	v_max3_f32 v0, v0, v59, v42
	v_max3_f32 v66, v66, v44, v45
	v_max3_f32 v0, v0, v43, v62
	v_max3_f32 v66, v66, v64, v65
	v_max3_f32 v0, v0, v63, v46
	v_max3_f32 v66, v66, v48, v49
	v_max3_f32 v0, v0, v47, v66
	v_mov_b32_e32 v66, v0
	s_nop 1
	v_permlane32_swap_b32_e32 v0, v66
	v_max_f32_e32 v0, v0, v66
	v_cmp_lt_f32_e32 vcc, s27, v0
	s_cmp_lg_u64 vcc, 0
	s_cselect_b64 s[4:5], -1, 0
	s_cbranch_vccnz .LBB0_584

.LBB0_537:
	s_mov_b64 s[4:5], 0x7e000
	v_lshl_add_u64 v[70:71], v[226:227], 0, s[4:5]
	s_mov_b32 m0, s84
	s_nop 0
	global_load_lds_dwordx4 v[70:71], off
	ds_read_b64_tr_b16 v[166:167], v228 offset:36864
	ds_read_b64_tr_b16 v[168:169], v228 offset:37376
	v_add_f32_e32 v70, v50, v51
	v_add_f32_e32 v70, v52, v70
	v_add_f32_e32 v70, v53, v70
	v_add_f32_e32 v70, v54, v70
	v_add_f32_e32 v86, v55, v70
	s_waitcnt lgkmcnt(9)
	v_mfma_f32_32x32x16_bf16 v[66:81], v[66:69], v[110:113], 0
	v_cvt_pk_bf16_f32 v134, v50, v51
	v_cvt_pk_bf16_f32 v135, v52, v53
	ds_read_b64_tr_b16 v[158:159], v228 offset:40960
	ds_read_b64_tr_b16 v[160:161], v228 offset:41472
	v_add_f32_e32 v50, v56, v86
	v_add_f32_e32 v50, v57, v50
	v_add_f32_e32 v50, v58, v50
	v_add_f32_e32 v50, v59, v50
	v_cvt_pk_bf16_f32 v136, v54, v55
	v_cvt_pk_bf16_f32 v137, v56, v57
	s_waitcnt lgkmcnt(10)
	v_mfma_f32_32x32x16_bf16 v[82:97], v[82:85], v[110:113], 0
	ds_read_b64_tr_b16 v[146:147], v228 offset:37888
	ds_read_b64_tr_b16 v[148:149], v228 offset:38400
	s_waitcnt lgkmcnt(11)
	v_mfma_f32_32x32x16_bf16 v[66:81], v[178:181], v[106:109], v[66:81]
	v_add_f32_e32 v50, v60, v50
	v_add_f32_e32 v50, v61, v50
	v_add_f32_e32 v50, v62, v50
	v_add_f32_e32 v50, v63, v50
	v_cvt_pk_bf16_f32 v130, v58, v59
	v_cvt_pk_bf16_f32 v131, v60, v61
	ds_read_b64_tr_b16 v[150:151], v228 offset:41984
	ds_read_b64_tr_b16 v[152:153], v228 offset:42496
	v_add_f32_e32 v50, v64, v50
	v_add_f32_e32 v50, v65, v50
	v_add_f32_e32 v50, v34, v50
	v_add_f32_e32 v50, v35, v50
	v_cvt_pk_bf16_f32 v132, v62, v63
	v_cvt_pk_bf16_f32 v133, v64, v65
	s_waitcnt lgkmcnt(12)
	v_mfma_f32_32x32x16_bf16 v[82:97], v[162:165], v[106:109], v[82:97]
	ds_read_b64_tr_b16 v[162:163], v228 offset:38912
	ds_read_b64_tr_b16 v[164:165], v228 offset:39424
	s_waitcnt lgkmcnt(13)
	v_mfma_f32_32x32x16_bf16 v[66:81], v[138:141], v[102:105], v[66:81]
	v_add_f32_e32 v50, v36, v50
	v_add_f32_e32 v50, v37, v50
	v_add_f32_e32 v50, v38, v50
	v_add_f32_e32 v50, v39, v50
	v_cvt_pk_bf16_f32 v122, v34, v35
	v_cvt_pk_bf16_f32 v123, v36, v37
	ds_read_b64_tr_b16 v[138:139], v228 offset:43008
	ds_read_b64_tr_b16 v[140:141], v228 offset:43520
	v_add_f32_e32 v34, v40, v50
	v_add_f32_e32 v34, v41, v34
	v_add_f32_e32 v34, v42, v34
	v_add_f32_e32 v34, v43, v34
	v_cvt_pk_bf16_f32 v124, v38, v39
	v_cvt_pk_bf16_f32 v125, v40, v41
	s_waitcnt lgkmcnt(14)
	v_mfma_f32_32x32x16_bf16 v[82:97], v[174:177], v[102:105], v[82:97]
	ds_read_b64_tr_b16 v[142:143], v228 offset:39936
	ds_read_b64_tr_b16 v[144:145], v228 offset:40448
	s_waitcnt lgkmcnt(14)
	v_mfma_f32_32x32x16_bf16 v[66:81], v[154:157], v[98:101], v[66:81]
	v_add_f32_e32 v34, v44, v34
	v_add_f32_e32 v34, v45, v34
	v_add_f32_e32 v34, v46, v34
	v_add_f32_e32 v34, v47, v34
	v_cvt_pk_bf16_f32 v118, v42, v43
	v_cvt_pk_bf16_f32 v119, v44, v45
	ds_read_b64_tr_b16 v[154:155], v228 offset:44032
	ds_read_b64_tr_b16 v[156:157], v228 offset:44544
	v_add_f32_e32 v34, v48, v34
	v_add_f32_e32 v34, v49, v34
	v_mfma_f32_32x32x16_bf16 v[82:97], v[170:173], v[98:101], v[82:97]
	v_add_f32_e32 v170, 0, v34
	v_cvt_pk_bf16_f32 v120, v46, v47
	v_cvt_pk_bf16_f32 v121, v48, v49
	ds_read_b128 v[34:37], v207 offset:20480
	v_add_f32_e32 v219, v184, v170
	s_waitcnt lgkmcnt(0)
	v_mfma_f32_32x32x16_bf16 v[66:81], v[34:37], v[114:117], v[66:81]
	ds_read_b128 v[34:37], v207 offset:20992
	s_waitcnt lgkmcnt(0)
	v_mfma_f32_32x32x16_bf16 v[82:97], v[34:37], v[114:117], v[82:97]
	ds_read_b128 v[34:37], v207 offset:22528
	s_waitcnt lgkmcnt(0)
	v_mfma_f32_32x32x16_bf16 v[66:81], v[34:37], v[126:129], v[66:81]
	ds_read_b128 v[34:37], v207 offset:23040
	s_waitcnt lgkmcnt(0)
	v_mfma_f32_32x32x16_bf16 v[82:97], v[34:37], v[126:129], v[82:97]
	s_nop 8
	v_add_f32_e64 v50, v66, -v224
	v_add_f32_e64 v51, v67, -v224
	v_add_f32_e64 v52, v68, -v224
	v_add_f32_e64 v53, v69, -v224
	v_add_f32_e64 v54, v70, -v224
	v_add_f32_e64 v55, v71, -v224
	v_pk_add_f32 v[56:57], v[72:73], v[224:225] op_sel_hi:[1,0] neg_lo:[0,1] neg_hi:[0,1]
	v_pk_add_f32 v[58:59], v[74:75], v[224:225] op_sel_hi:[1,0] neg_lo:[0,1] neg_hi:[0,1]
	v_pk_add_f32 v[60:61], v[76:77], v[224:225] op_sel_hi:[1,0] neg_lo:[0,1] neg_hi:[0,1]
	v_pk_add_f32 v[62:63], v[78:79], v[224:225] op_sel_hi:[1,0] neg_lo:[0,1] neg_hi:[0,1]
	v_pk_add_f32 v[34:35], v[82:83], v[224:225] op_sel_hi:[1,0] neg_lo:[0,1] neg_hi:[0,1]
	v_pk_add_f32 v[36:37], v[84:85], v[224:225] op_sel_hi:[1,0] neg_lo:[0,1] neg_hi:[0,1]
	v_pk_add_f32 v[38:39], v[86:87], v[224:225] op_sel_hi:[1,0] neg_lo:[0,1] neg_hi:[0,1]
	v_pk_add_f32 v[40:41], v[88:89], v[224:225] op_sel_hi:[1,0] neg_lo:[0,1] neg_hi:[0,1]
	v_pk_add_f32 v[42:43], v[90:91], v[224:225] op_sel_hi:[1,0] neg_lo:[0,1] neg_hi:[0,1]
	v_pk_add_f32 v[44:45], v[92:93], v[224:225] op_sel_hi:[1,0] neg_lo:[0,1] neg_hi:[0,1]
	v_pk_add_f32 v[46:47], v[94:95], v[224:225] op_sel_hi:[1,0] neg_lo:[0,1] neg_hi:[0,1]
	v_pk_add_f32 v[64:65], v[80:81], v[224:225] op_sel_hi:[1,0] neg_lo:[0,1] neg_hi:[0,1]
	v_pk_add_f32 v[48:49], v[96:97], v[224:225] op_sel_hi:[1,0] neg_lo:[0,1] neg_hi:[0,1]
	s_cmp_lg_u32 0, -1
	s_cselect_b32 s4, 0, 0
	s_add_i32 s6, s4, s85
	v_lshl_add_u64 v[66:67], v[182:183], 0, s[40:41]
	s_add_i32 s4, s6, 0x3000
	s_mov_b32 m0, s4
	s_nop 0
	global_load_lds_dwordx4 v[66:67], off
	s_mov_b64 s[4:5], 0x1f4000
	v_lshl_add_u64 v[66:67], v[222:223], 0, s[4:5]
	s_add_i32 s6, s6, 0xf000
	s_mov_b32 m0, s6
	s_nop 0
	global_load_lds_dwordx4 v[66:67], off
	v_max_f32_e32 v66, v50, v51
	v_max3_f32 v67, v52, v53, v35
	v_max3_f32 v66, v66, v34, v36
	v_max3_f32 v66, v66, v37, v54
	v_max3_f32 v67, v67, v56, v57
	v_max3_f32 v66, v66, v55, v38
	v_max3_f32 v67, v67, v40, v41
	v_max3_f32 v66, v66, v39, v58
	v_max3_f32 v67, v67, v60, v61
	v_max3_f32 v66, v66, v59, v42
	v_max3_f32 v67, v67, v44, v45
	v_max3_f32 v66, v66, v43, v62
	v_max3_f32 v67, v67, v64, v65
	v_max3_f32 v66, v66, v63, v46
	v_max3_f32 v67, v67, v48, v49
	v_max3_f32 v66, v66, v47, v67
	v_mov_b32_e32 v67, v66
	s_nop 1
	v_permlane32_swap_b32_e32 v66, v67
	v_max_f32_e32 v66, v66, v67
	v_cmp_lt_f32_e32 vcc, s27, v66
	s_cmp_lg_u64 vcc, 0
	s_cselect_b64 s[4:5], -1, 0
	s_cbranch_vccnz .LBB0_587
